# attention inner loop hand-rewritten (intra-wave MFMA/softmax interleave, in-place softmax, max folded into QK accumulator init) + faster XCD-local barrier
# speedup vs baseline: 1.0188x; 1.0188x over previous
; #define LAS __attribute__((address_space(3)))
; __global__ void __launch_bounds__(512, 2) trunk_fwd(Args args) {
;     extern __shared__ __attribute__((aligned(16))) unsigned char lds_raw[];
;     LAS unsigned char* lds = (LAS unsigned char*)lds_raw;
;     volatile LAS unsigned* MISC = (volatile LAS unsigned*)(lds + MISC_OFF);
;     for (int u = threadIdx.x; u < 32; u += 512) MISC[u] = (u == 16) ? blockIdx.x : 0u;
;     __syncthreads();
;     XcdBarrier bar = xcd_barrier_post((unsigned*)(args.ws + WS_CTL) + 1024, MISC + 8);
_Z9trunk_fwd4Args:
	s_mov_b32 s101, 0
	s_mov_b64 s[94:95], s[0:1]
	s_load_dwordx2 s[0:1], s[0:1], 0xc0
	v_and_b32_e32 v163, 0x3ff, v0
	v_cmp_gt_u32_e32 vcc, 32, v163
	s_and_saveexec_b64 s[4:5], vcc
	s_cbranch_execz .LBB0_2
	v_mov_b32_e32 v1, s2
	v_cmp_eq_u32_e32 vcc, 16, v163
	v_lshl_add_u32 v2, v163, 2, 0
	v_add_u32_e32 v2, 0x20140, v2
	v_cndmask_b32_e32 v1, 0, v1, vcc
	ds_write_b32 v2, v1

; __device__ __forceinline__ unsigned xb_ld(unsigned* p)              { return __hip_atomic_load(p, __ATOMIC_RELAXED, __HIP_MEMORY_SCOPE_AGENT); }
; __device__ __forceinline__ unsigned xb_add(unsigned* p, unsigned v) { return __hip_atomic_fetch_add(p, v, __ATOMIC_RELAXED, __HIP_MEMORY_SCOPE_AGENT); }
; #define XB_SPIN(cond, bar) do { unsigned _sp = 0; while (cond) { __builtin_amdgcn_s_sleep(1); \
;     if ((++_sp & 255u) == 0u) { if (xb_ld(&(bar)[XB_TMO])) break; if (_sp > XB_SPIN_CAP) { atomicAdd(&(bar)[XB_TMO], 1u); break; } } } } while (0)
; __device__ __forceinline__ void xcd_local_barrier(const XcdBarrier& b, unsigned nloc) {
;     asm volatile("s_waitcnt vmcnt(0)" ::: "memory");
;     __syncthreads();
;     if (threadIdx.x == 0) {
;         unsigned* bar = b.bar;
;         __builtin_amdgcn_s_waitcnt(0);
;         const unsigned old = xb_add(&bar[XB_LSUB(b.x)], 1u);
;         const unsigned gen = old / nloc;
;         if (old + 1u == (gen + 1u) * nloc) xb_add(&bar[XB_LGEN(b.x)], 1u);
;         else XB_SPIN(xb_ld(&bar[XB_LGEN(b.x)]) == gen, bar);
;         __builtin_amdgcn_fence(__ATOMIC_ACQUIRE, "agent");
;         asm volatile("s_waitcnt vmcnt(0)" ::: "memory");
;     }
;     __syncthreads();
; }
.LBB0_507:
	v_readlane_b32 s4, v254, 60
	v_mov_b32 v0, s4
	ds_read_b32 v0, v0
	s_waitcnt lgkmcnt(0)
	s_nop 0
	v_readfirstlane_b32 s4, v0
	s_cmp_eq_u32 s4, 0
	s_cbranch_scc1 .LBB0_521
	s_waitcnt vmcnt(0)
	s_waitcnt lgkmcnt(0)
	s_barrier
	s_and_saveexec_b64 s[18:19], s[92:93]
	v_readlane_b32 s6, v255, 17
	v_readlane_b32 s7, v255, 18
	s_cbranch_execz .LBB0_527
	s_add_u32 s101, s101, 32
	v_readlane_b32 s4, v254, 6
	v_readlane_b32 s5, v254, 7
	s_mov_b32 s100, 0
	s_nop 3
	global_atomic_add v1, v218, s[4:5]
	buffer_inv sc1
.Llb_spin_0:
	global_load_dword v2, v1, s[4:5] sc1
	s_waitcnt vmcnt(0)
	v_cmp_le_u32_e32 vcc, s101, v2
	s_cbranch_vccnz .Llb_done_0
	s_sleep 1
	s_add_u32 s100, s100, 1
	s_cmp_lt_u32 s100, 0x4000
	s_cbranch_scc1 .Llb_spin_0
.Llb_done_0:
	s_branch .LBB0_527
.LBB0_521:
	v_readlane_b32 s6, v255, 17
	v_readlane_b32 s7, v255, 18
	s_cbranch_execnz .LBB0_528
	s_branch .LBB0_581
.LBB0_527:
	s_or_b64 exec, exec, s[18:19]
	s_barrier
	s_branch .LBB0_581

; __device__ __forceinline__ unsigned xb_ld(unsigned* p)              { return __hip_atomic_load(p, __ATOMIC_RELAXED, __HIP_MEMORY_SCOPE_AGENT); }
; __device__ __forceinline__ unsigned xb_add(unsigned* p, unsigned v) { return __hip_atomic_fetch_add(p, v, __ATOMIC_RELAXED, __HIP_MEMORY_SCOPE_AGENT); }
; #define XB_SPIN(cond, bar) do { unsigned _sp = 0; while (cond) { __builtin_amdgcn_s_sleep(1); \
;     if ((++_sp & 255u) == 0u) { if (xb_ld(&(bar)[XB_TMO])) break; if (_sp > XB_SPIN_CAP) { atomicAdd(&(bar)[XB_TMO], 1u); break; } } } } while (0)
; __device__ __forceinline__ void xcd_local_barrier(const XcdBarrier& b, unsigned nloc) {
;     asm volatile("s_waitcnt vmcnt(0)" ::: "memory");
;     __syncthreads();
;     if (threadIdx.x == 0) {
;         unsigned* bar = b.bar;
;         __builtin_amdgcn_s_waitcnt(0);
;         const unsigned old = xb_add(&bar[XB_LSUB(b.x)], 1u);
;         const unsigned gen = old / nloc;
;         if (old + 1u == (gen + 1u) * nloc) xb_add(&bar[XB_LGEN(b.x)], 1u);
;         else XB_SPIN(xb_ld(&bar[XB_LGEN(b.x)]) == gen, bar);
;         __builtin_amdgcn_fence(__ATOMIC_ACQUIRE, "agent");
;         asm volatile("s_waitcnt vmcnt(0)" ::: "memory");
;     }
;     __syncthreads();
; }
.LBB0_731:
	v_readlane_b32 s0, v254, 60
	v_mov_b32 v0, s0
	ds_read_b32 v0, v0
	s_waitcnt lgkmcnt(0)
	s_nop 0
	v_readfirstlane_b32 s0, v0
	s_cmp_eq_u32 s0, 0
	s_cbranch_scc1 .LBB0_745
	s_waitcnt vmcnt(0)
	s_waitcnt vmcnt(0) lgkmcnt(0)
	s_barrier
	s_and_saveexec_b64 s[0:1], s[92:93]
	v_readlane_b32 s6, v255, 17
	v_readlane_b32 s7, v255, 18
	s_cbranch_execz .LBB0_751
	s_add_u32 s101, s101, 32
	v_readlane_b32 s4, v254, 6
	v_readlane_b32 s5, v254, 7
	s_mov_b32 s100, 0
	s_nop 3
	global_atomic_add v1, v218, s[4:5]
	buffer_inv sc1

; __device__ __forceinline__ unsigned xb_ld(unsigned* p)              { return __hip_atomic_load(p, __ATOMIC_RELAXED, __HIP_MEMORY_SCOPE_AGENT); }
; __device__ __forceinline__ unsigned xb_add(unsigned* p, unsigned v) { return __hip_atomic_fetch_add(p, v, __ATOMIC_RELAXED, __HIP_MEMORY_SCOPE_AGENT); }
; #define XB_SPIN(cond, bar) do { unsigned _sp = 0; while (cond) { __builtin_amdgcn_s_sleep(1); \
;     if ((++_sp & 255u) == 0u) { if (xb_ld(&(bar)[XB_TMO])) break; if (_sp > XB_SPIN_CAP) { atomicAdd(&(bar)[XB_TMO], 1u); break; } } } } while (0)
; __device__ __forceinline__ void xcd_local_barrier(const XcdBarrier& b, unsigned nloc) {
;     asm volatile("s_waitcnt vmcnt(0)" ::: "memory");
;     __syncthreads();
;     if (threadIdx.x == 0) {
;         unsigned* bar = b.bar;
;         __builtin_amdgcn_s_waitcnt(0);
;         const unsigned old = xb_add(&bar[XB_LSUB(b.x)], 1u);
;         const unsigned gen = old / nloc;
;         if (old + 1u == (gen + 1u) * nloc) xb_add(&bar[XB_LGEN(b.x)], 1u);
;         else XB_SPIN(xb_ld(&bar[XB_LGEN(b.x)]) == gen, bar);
;         __builtin_amdgcn_fence(__ATOMIC_ACQUIRE, "agent");
;         asm volatile("s_waitcnt vmcnt(0)" ::: "memory");
;     }
;     __syncthreads();
; }
.Llb_done_1:
	s_branch .LBB0_751
.LBB0_745:
	v_readlane_b32 s6, v255, 17
	v_readlane_b32 s7, v255, 18
	s_cbranch_execnz .LBB0_752
	s_branch .LBB0_805
.LBB0_751:
	s_or_b64 exec, exec, s[0:1]
	s_barrier
	s_branch .LBB0_805

; #define LAS __attribute__((address_space(3)))
; #define SBAR() __builtin_amdgcn_sched_barrier(0)
; #define WAIT_BAR(N) asm volatile("s_waitcnt vmcnt(" #N ") lgkmcnt(0)\n\ts_barrier" ::: "memory")
; __device__ __forceinline__ void attn_unit(int b, int h, int qb, const bf16* Q, const bf16* __restrict__ Kn, const bf16* __restrict__ Kpe, const bf16* __restrict__ V, bf16* O, float* ASS, LAS char* shm) {
;     int tid_ = threadIdx.x; asm volatile("" : "+v"(tid_));
;     const int tid = tid_, lane = tid & 63, r32 = lane & 31, hi = lane >> 5; const int wid = __builtin_amdgcn_readfirstlane(tid >> 6);
;     const long rowbase = (long)b * SEQ; const int q0 = qb * QB;
;     const bf16* Qw = Q + (rowbase + q0 + wid * QBLK) * QP + h * 96;
;     const unsigned lds0 = (unsigned)(uintptr_t)shm;
;     LAS float* wsf = (LAS float*)(shm + LDS_WS) + wid * 64;
;     const bf16* ksrc = Kn + (rowbase + lane) * KNP + h * 64 + wid * 8;
;     const bf16* k2src = Kpe + (rowbase + lane) * KPP + (wid & 3) * 8;
;     const bf16* vsrc = V + (rowbase + 16 * (wid & 3) + (lane >> 2)) * VP + h * 64 + (wid >> 2) * 32 + (lane & 3) * 8;
;     const unsigned kdst = lds0 + LDS_K + wid * 1024, k2dst = lds0 + LDS_K + (8 + (wid & 3)) * 1024, vdst = lds0 + LDS_V + wid * 1024;
;     ...
;     const int vb0 = (int)(lds0 + LDS_V) + ((lane >> 4) & 1) * 32 + (lane & 3) * 8 + (4 * hi + ((lane & 15) >> 2)) * 64;
;     const int NT = (q0 + QB) / KVBLK;
;     DMA_TILE(0, 0, 0); DMA_TILE(1, 1, 1);
;     bf16x8 qr[6];
; #pragma unroll
;     for (int d0 = 0; d0 < 6; ++d0) qr[d0] = *reinterpret_cast<const bf16x8*>(&Qw[(long)r32 * QP + d0 * 16 + hi * 8]);
;     asm volatile("" : "+v"(qr[0]), "+v"(qr[1]), "+v"(qr[2]), "+v"(qr[3]), "+v"(qr[4]), "+v"(qr[5]));
;     float m_run = -1e30f, l_run = 0.f; f32x16 o[2]; o[0] = f32x16{}; o[1] = f32x16{};
;     const int qrel = wid * QBLK + r32;
;     f32x16 p0, p1;
;     ...
;         for (int t = 0; t < NT; ++t) {
;             if (t + 1 < NT) { WAIT_BAR(3); } else { WAIT_BAR(0); }
;             if (t > 0) V_LOAD((vs + 3) & 3);
;             if (t + 2 < NT) DMA_TILE(t + 2, (ks == 0) ? 2 : ks - 1, (vs + 2) & 3);
;             SBAR();
;             if (t > 0) SOFTMAX();
;             K_LOAD(ks);
;             if (t > 0) PV_MMA();
;             QK_MMA(t);
.LBB0_870:
	v_mov_b32_e32 v138, v163
	s_or_b32 s68, s38, s75
	v_readfirstlane_b32 s4, v138
	s_ashr_i32 s69, s4, 6
	s_lshl_b32 s5, s69, 5
	s_ashr_i32 s38, s5, 31
	s_add_u32 s66, s84, s5
	s_addc_u32 s67, s85, s38
	s_mul_i32 s38, s67, 0x600
	s_mul_hi_u32 s39, s66, 0x600
	s_add_i32 s39, s39, s38
	s_mul_i32 s38, s66, 0x600
	v_and_b32_e32 v139, 63, v138
	s_add_u32 s38, s78, s38
	s_mul_i32 s48, s68, 0x60
	s_addc_u32 s39, s79, s39
	s_lshl_b64 s[64:65], s[48:49], 1
	v_or_b32_e32 v6, s42, v139
	v_mov_b32_e32 v7, s43
	s_add_u32 s38, s38, s64
	s_waitcnt lgkmcnt(0)
	v_lshlrev_b64 v[2:3], 10, v[6:7]
	s_addc_u32 s39, s39, s65
	v_lshl_add_u64 v[2:3], s[0:1], 0, v[2:3]
	s_lshl_b32 s48, s68, 7
	s_lshl_b32 s46, s69, 3
	v_lshl_add_u64 v[2:3], v[2:3], 0, s[48:49]
	s_ashr_i32 s47, s46, 31
	s_and_b32 s50, s69, 3
	v_lshl_add_u64 v[2:3], s[46:47], 1, v[2:3]
	s_lshl_b32 s46, s50, 4
	v_bfe_u32 v0, v138, 2, 4
	v_lshlrev_b64 v[4:5], 6, v[6:7]
	v_or_b32_e32 v0, s46, v0
	v_lshl_add_u64 v[4:5], s[18:19], 0, v[4:5]
	s_mov_b32 s47, s49
	v_or_b32_e32 v6, s42, v0
	v_lshl_add_u64 v[4:5], v[4:5], 0, s[46:47]
	v_lshlrev_b64 v[6:7], 10, v[6:7]
	s_ashr_i32 s46, s4, 3
	v_lshl_add_u64 v[6:7], s[40:41], 0, v[6:7]
	s_andn2_b32 s46, s46, 31
	v_lshl_add_u64 v[6:7], v[6:7], 0, s[48:49]
	s_ashr_i32 s47, s46, 31
	v_lshlrev_b32_e32 v0, 3, v138
	s_lshl_b32 s48, s69, 10
	s_lshl_b32 s50, s50, 10
	v_lshl_add_u64 v[6:7], s[46:47], 1, v[6:7]
	v_and_b32_e32 v10, 24, v0
	s_add_i32 s97, s48, 0
	s_bitset1_b32 s50, 13
	s_mov_b32 s46, m0
	s_mov_b32 m0, s97
	s_nop 0
	global_load_lds_dwordx4 v[2:3], off
	s_mov_b32 m0, s46
	v_lshlrev_b32_e32 v0, 1, v10
	s_add_i32 s72, s50, 0
	s_mov_b32 s46, m0
	s_mov_b32 m0, s72
	s_nop 0
	global_load_lds_dwordx4 v[4:5], off
	s_mov_b32 m0, s46
	v_and_b32_e32 v140, 31, v138
	v_lshl_add_u64 v[6:7], v[6:7], 0, v[0:1]
	s_add_i32 s73, s97, 0x9000
	s_mov_b32 s46, m0
	s_mov_b32 m0, s73
	s_nop 0
	global_load_lds_dwordx4 v[6:7], off
	s_mov_b32 m0, s46
	v_lshl_add_u64 v[8:9], v[2:3], 0, s[34:35]
	s_add_i32 s46, s48, s33
	s_mov_b32 s47, m0
	s_mov_b32 m0, s46
	s_nop 0
	global_load_lds_dwordx4 v[8:9], off
	s_mov_b32 m0, s47
	v_mul_u32_u24_e32 v0, 0x300, v140
	v_bfe_u32 v141, v138, 5, 1
	v_lshl_add_u64 v[8:9], v[4:5], 0, s[20:21]
	s_add_i32 s46, s50, s33
	s_mov_b32 s47, m0
	s_mov_b32 m0, s46
	s_nop 0
	global_load_lds_dwordx4 v[8:9], off
	s_mov_b32 m0, s47
	v_lshlrev_b32_e32 v0, 1, v0
	v_lshl_add_u64 v[8:9], v[6:7], 0, s[34:35]
	s_add_i32 s46, s97, 0xb000
	s_mov_b32 s47, m0
	s_mov_b32 m0, s46
	s_nop 0
	global_load_lds_dwordx4 v[8:9], off
	s_mov_b32 m0, s47
	v_lshl_or_b32 v0, v141, 4, v0
	global_load_dwordx4 v[80:83], v0, s[38:39] offset:160
	global_load_dwordx4 v[84:87], v0, s[38:39] offset:128
	global_load_dwordx4 v[88:91], v0, s[38:39] offset:96
	global_load_dwordx4 v[92:95], v0, s[38:39] offset:64
	global_load_dwordx4 v[96:99], v0, s[38:39] offset:32
	global_load_dwordx4 v[100:103], v0, s[38:39]
	s_and_b32 s4, s4, 0x3fffffc0
	v_lshlrev_b32_e32 v0, 1, v138
	s_lshl_b32 s4, s4, 2
	v_lshlrev_b32_e32 v8, 4, v138
	v_and_b32_e32 v0, 32, v0
	s_add_i32 s96, s4, 0
	v_lshlrev_b32_e32 v9, 8, v141
	v_and_b32_e32 v8, 0xc0, v8
	v_lshlrev_b32_e32 v11, 10, v141
	v_lshlrev_b32_e32 v12, 4, v140
	v_add3_u32 v0, 0, v0, v10
	s_add_i32 s96, s96, 0x11000
	v_cmp_gt_u32_e64 s[38:39], 32, v139
	v_lshlrev_b32_e32 v143, 4, v141
	v_add3_u32 v146, 0, v11, v12
	v_or_b32_e32 v145, s5, v140
	v_add3_u32 v144, v0, v9, v8
	v_lshl_add_u64 v[132:133], v[2:3], 0, s[2:3]
	v_lshl_add_u64 v[134:135], v[4:5], 0, s[22:23]
	s_cmp_lt_i32 s69, 4
	v_lshl_add_u32 v142, v140, 2, s96
	v_lshl_add_u64 v[136:137], v[6:7], 0, s[2:3]
	s_mov_b64 s[46:47], -1
	s_waitcnt vmcnt(0)
	s_waitcnt vmcnt(3) lgkmcnt(0)
	s_barrier
	s_add_i32 s4, 0, 0x6000
	v_lshl_add_u64 v[8:9], v[2:3], 0, s[2:3]
	s_add_i32 s48, s48, s4
	s_mov_b32 s5, m0
	s_mov_b32 m0, s48
	s_nop 0
	global_load_lds_dwordx4 v[8:9], off
	s_mov_b32 m0, s5
	v_lshl_add_u64 v[8:9], v[4:5], 0, s[22:23]
	s_add_i32 s50, s50, s4
	s_mov_b32 s4, m0
	s_mov_b32 m0, s50
	s_nop 0
	global_load_lds_dwordx4 v[8:9], off
	s_mov_b32 m0, s4
	v_lshl_add_u64 v[8:9], v[6:7], 0, s[2:3]
	s_add_i32 s4, s97, 0xd000
	s_mov_b32 s5, m0
	s_mov_b32 m0, s4
	s_nop 0
	global_load_lds_dwordx4 v[8:9], off
	s_mov_b32 m0, s5
	ds_read_b128 v[8:11], v146
	ds_read_b128 v[12:15], v146 offset:512
	ds_read_b128 v[16:19], v146 offset:2048
	ds_read_b128 v[20:23], v146 offset:2560
	ds_read_b128 v[24:27], v146 offset:4096
	ds_read_b128 v[28:31], v146 offset:4608
	ds_read_b128 v[32:35], v146 offset:6144
	ds_read_b128 v[36:39], v146 offset:6656
	ds_read_b128 v[40:43], v146 offset:8192
	ds_read_b128 v[44:47], v146 offset:8704
	ds_read_b128 v[104:107], v146 offset:10240
	ds_read_b128 v[108:111], v146 offset:10752
	s_waitcnt lgkmcnt(11)
	v_mfma_f32_32x32x16_bf16 v[64:79], v[8:11], v[100:103], 0
	s_mov_b32 s48, s49
	s_mov_b32 s50, s49
	s_mov_b32 s51, s49
	s_mov_b32 s52, s49
	s_mov_b32 s53, s49
	s_mov_b32 s54, s49
	s_mov_b32 s55, s49
	s_waitcnt lgkmcnt(10)
	v_mfma_f32_32x32x16_bf16 v[48:63], v[12:15], v[100:103], 0
	s_mov_b32 s56, s49
	s_mov_b32 s57, s49
	s_mov_b32 s58, s49
	s_mov_b32 s59, s49
	s_mov_b32 s60, s49
	s_mov_b32 s61, s49
	s_mov_b32 s62, s49
	s_waitcnt lgkmcnt(9)
	v_mfma_f32_32x32x16_bf16 v[64:79], v[16:19], v[96:99], v[64:79]
	s_mov_b32 s63, s49
	s_waitcnt lgkmcnt(8)
	v_mfma_f32_32x32x16_bf16 v[48:63], v[20:23], v[96:99], v[48:63]
	s_waitcnt lgkmcnt(7)
	v_mfma_f32_32x32x16_bf16 v[64:79], v[24:27], v[92:95], v[64:79]
	s_waitcnt lgkmcnt(6)
	v_mfma_f32_32x32x16_bf16 v[48:63], v[28:31], v[92:95], v[48:63]
	v_mov_b64_e32 v[16:17], s[48:49]
	v_mov_b64_e32 v[18:19], s[50:51]
	v_mov_b64_e32 v[20:21], s[52:53]
	v_mov_b64_e32 v[22:23], s[54:55]
	v_mov_b64_e32 v[24:25], s[56:57]
	v_mov_b64_e32 v[26:27], s[58:59]
	v_mov_b64_e32 v[28:29], s[60:61]
	s_waitcnt lgkmcnt(5)
	v_mfma_f32_32x32x16_bf16 v[64:79], v[32:35], v[88:91], v[64:79]
	v_mov_b64_e32 v[30:31], s[62:63]
	s_waitcnt lgkmcnt(4)
	v_mfma_f32_32x32x16_bf16 v[48:63], v[36:39], v[88:91], v[48:63]
	s_waitcnt lgkmcnt(3)
	v_mfma_f32_32x32x16_bf16 v[64:79], v[40:43], v[84:87], v[64:79]
	s_waitcnt lgkmcnt(2)
	v_mfma_f32_32x32x16_bf16 v[48:63], v[44:47], v[84:87], v[48:63]
	s_waitcnt lgkmcnt(1)
	v_mfma_f32_32x32x16_bf16 v[64:79], v[104:107], v[80:83], v[64:79]
	s_waitcnt lgkmcnt(0)
	v_mfma_f32_32x32x16_bf16 v[48:63], v[108:111], v[80:83], v[48:63]
	s_mov_b64 s[4:5], 0x30000
	v_mov_b64_e32 v[46:47], v[30:31]
	v_lshl_add_u32 v0, v141, 2, s92
	v_lshl_add_u64 v[14:15], v[4:5], 0, s[6:7]
	v_lshl_add_u64 v[124:125], v[6:7], 0, s[4:5]
	v_lshl_add_u64 v[126:127], v[2:3], 0, s[4:5]
	s_mov_b32 s48, 1
	v_mov_b32_e32 v128, 0
	v_mov_b32_e32 v130, 0xf149f2ca
	v_mov_b64_e32 v[44:45], v[28:29]
	v_mov_b64_e32 v[42:43], v[26:27]
	v_mov_b64_e32 v[40:41], v[24:25]
	v_mov_b64_e32 v[38:39], v[22:23]
	v_mov_b64_e32 v[36:37], v[20:21]
	v_mov_b64_e32 v[34:35], v[18:19]
	v_mov_b64_e32 v[32:33], v[16:17]
	s_mov_b32 s50, 1
	s_mov_b32 s52, 1
	s_add_i32 s51, s52, 1
	s_cmp_ge_u32 s51, s86
	s_mov_b64 s[46:47], -1
	s_branch .Lat_u1_entry
; __device__ __forceinline__ float max3f(float a, float b, float c) { return __builtin_fmaxf(__builtin_fmaxf(a, b), c); }
; __device__ __forceinline__ float rowmax(const f32x16& p0, const f32x16& p1) {
;     float a = max3f(p0[0], p0[1], p1[0]), b = max3f(p0[2], p0[3], p1[1]); a = max3f(a, p1[2], p1[3]);
; #pragma unroll
;     for (int r = 4; r < 16; r += 4) { a = max3f(a, p0[r], p0[r + 1]); b = max3f(b, p0[r + 2], p0[r + 3]); a = max3f(a, p1[r], p1[r + 1]); b = max3f(b, p1[r + 2], p1[r + 3]); }
;     const float m = __builtin_fmaxf(a, b);
;     auto rr = __builtin_amdgcn_permlane32_swap(__float_as_uint(m), __float_as_uint(m), false, false);
;     return __builtin_fmaxf(__uint_as_float(rr[0]), __uint_as_float(rr[1]));
; }
.Lat_u1_entry:
	s_mov_b32 s54, m0
	s_nop 7
	s_nop 7
	v_max3_f32 v129, v64, v65, v66
	v_max3_f32 v131, v67, v68, v69
	v_max3_f32 v129, v129, v70, v71
	v_max3_f32 v131, v131, v72, v73
	v_max3_f32 v129, v129, v74, v75
	v_max3_f32 v131, v131, v76, v77
	v_max3_f32 v129, v129, v78, v79
	v_max3_f32 v131, v131, v48, v49
	v_max3_f32 v129, v129, v50, v51
	v_max3_f32 v131, v131, v52, v53
	v_max3_f32 v129, v129, v54, v55
	v_max3_f32 v131, v131, v56, v57
	v_max3_f32 v129, v129, v58, v59
	v_max3_f32 v131, v131, v60, v61
	v_max3_f32 v129, v129, v62, v63
	v_max_f32_e32 v129, v129, v131
	v_mov_b32_e32 v131, v129
	s_nop 1
	v_permlane32_swap_b32_e32 v129, v131
	s_nop 0
	v_max_f32_e32 v129, v129, v131
	v_mov_b32_e32 v130, v129
	v_sub_f32_e32 v104, 0, v129
	v_sub_f32_e32 v105, 0, v129
	v_sub_f32_e32 v106, 0, v129
	v_sub_f32_e32 v107, 0, v129
	v_sub_f32_e32 v108, 0, v129
	v_sub_f32_e32 v109, 0, v129
	v_sub_f32_e32 v110, 0, v129
	v_sub_f32_e32 v111, 0, v129
	v_sub_f32_e32 v112, 0, v129
	v_sub_f32_e32 v113, 0, v129
	v_sub_f32_e32 v114, 0, v129
	v_sub_f32_e32 v115, 0, v129
	v_sub_f32_e32 v116, 0, v129
	v_sub_f32_e32 v117, 0, v129
	v_sub_f32_e32 v118, 0, v129
	v_sub_f32_e32 v119, 0, v129
	v_sub_f32_e32 v64, v64, v129
	v_sub_f32_e32 v65, v65, v129
	v_sub_f32_e32 v66, v66, v129
	v_sub_f32_e32 v67, v67, v129
	v_sub_f32_e32 v68, v68, v129
	v_sub_f32_e32 v69, v69, v129
	v_sub_f32_e32 v70, v70, v129
	v_sub_f32_e32 v71, v71, v129
	v_sub_f32_e32 v72, v72, v129
	v_sub_f32_e32 v73, v73, v129
	v_sub_f32_e32 v74, v74, v129
	v_sub_f32_e32 v75, v75, v129
	v_sub_f32_e32 v76, v76, v129
	v_sub_f32_e32 v77, v77, v129
	v_sub_f32_e32 v78, v78, v129
	v_sub_f32_e32 v79, v79, v129
	v_sub_f32_e32 v48, v48, v129
	v_sub_f32_e32 v49, v49, v129
	v_sub_f32_e32 v50, v50, v129
	v_sub_f32_e32 v51, v51, v129
	v_sub_f32_e32 v52, v52, v129
	v_sub_f32_e32 v53, v53, v129
	v_sub_f32_e32 v54, v54, v129
	v_sub_f32_e32 v55, v55, v129
	v_sub_f32_e32 v56, v56, v129
	v_sub_f32_e32 v57, v57, v129
	v_sub_f32_e32 v58, v58, v129
	v_sub_f32_e32 v59, v59, v129
	v_sub_f32_e32 v60, v60, v129
	v_sub_f32_e32 v61, v61, v129
	v_sub_f32_e32 v62, v62, v129
	v_sub_f32_e32 v63, v63, v129
.Lat_u1_loop:
	s_add_i32 s4, s52, 1
	s_cmp_ge_u32 s4, s86
	s_cbranch_scc1 .Lat_u1x_lw
	s_waitcnt vmcnt(3) lgkmcnt(0)
	s_branch .Lat_u1x_bar

.Lat_u1x_bar:
	s_barrier
	s_mul_i32 s53, s48, 0x3000
	v_add_u32_e32 v158, s53, v146
	ds_read_b128 v[196:199], v158
	ds_read_b128 v[200:203], v158 offset:512
	ds_read_b128 v[204:207], v158 offset:2048
	ds_read_b128 v[208:211], v158 offset:2560
	ds_read_b128 v[212:215], v158 offset:4096
	ds_read_b128 v[230:233], v158 offset:4608
	ds_read_b128 v[234:237], v158 offset:6144
	ds_read_b128 v[164:167], v158 offset:6656
	ds_read_b128 v[168:171], v158 offset:8192
	ds_read_b128 v[172:175], v158 offset:8704
	ds_read_b128 v[148:151], v158 offset:10240
	ds_read_b128 v[152:155], v158 offset:10752
	s_lshl_b32 s4, s50, 13
	s_add_i32 s4, s4, 0x6000
	s_and_b32 s4, s4, 0x6000
	v_add_u32_e32 v159, s4, v144
	v_mov_b32_e32 v156, 0
	v_mov_b32_e32 v157, 0
	s_waitcnt lgkmcnt(11)
	v_mfma_f32_32x32x16_bf16 v[238:253], v[196:199], v[100:103], v[104:119]
	ds_read_b64_tr_b16 v[196:197], v159 offset:36864
	ds_read_b64_tr_b16 v[198:199], v159 offset:37376
	v_exp_f32_e32 v64, v64
	v_exp_f32_e32 v65, v65
	v_add_f32_e32 v156, v156, v64
	v_add_f32_e32 v156, v156, v65
	v_cvt_pk_bf16_f32 v64, v64, v65
	s_waitcnt lgkmcnt(12)
	v_mfma_f32_32x32x16_bf16 v[180:195], v[200:203], v[100:103], v[104:119]
	ds_read_b64_tr_b16 v[200:201], v159 offset:37888
	ds_read_b64_tr_b16 v[202:203], v159 offset:38400
	v_exp_f32_e32 v66, v66
	v_exp_f32_e32 v67, v67
	v_add_f32_e32 v157, v157, v66
	v_add_f32_e32 v157, v157, v67
	v_cvt_pk_bf16_f32 v65, v66, v67
	s_waitcnt lgkmcnt(13)
	v_mfma_f32_32x32x16_bf16 v[238:253], v[204:207], v[96:99], v[238:253]
	ds_read_b64_tr_b16 v[204:205], v159 offset:38912
	ds_read_b64_tr_b16 v[206:207], v159 offset:39424
	v_exp_f32_e32 v68, v68
	v_exp_f32_e32 v69, v69
	v_add_f32_e32 v156, v156, v68
	v_add_f32_e32 v156, v156, v69
	v_cvt_pk_bf16_f32 v66, v68, v69
	s_waitcnt lgkmcnt(14)
	v_mfma_f32_32x32x16_bf16 v[180:195], v[208:211], v[96:99], v[180:195]
	ds_read_b64_tr_b16 v[208:209], v159 offset:39936
	ds_read_b64_tr_b16 v[210:211], v159 offset:40448
	v_exp_f32_e32 v70, v70
	v_exp_f32_e32 v71, v71
	v_add_f32_e32 v157, v157, v70
	v_add_f32_e32 v157, v157, v71
	v_cvt_pk_bf16_f32 v67, v70, v71
	s_waitcnt lgkmcnt(15)
	v_mfma_f32_32x32x16_bf16 v[238:253], v[212:215], v[92:95], v[238:253]
	ds_read_b64_tr_b16 v[212:213], v159 offset:40960
	ds_read_b64_tr_b16 v[214:215], v159 offset:41472
	v_exp_f32_e32 v72, v72
	v_exp_f32_e32 v73, v73
	v_add_f32_e32 v156, v156, v72
	v_add_f32_e32 v156, v156, v73
	v_cvt_pk_bf16_f32 v68, v72, v73
	s_waitcnt lgkmcnt(15)
	v_mfma_f32_32x32x16_bf16 v[180:195], v[230:233], v[92:95], v[180:195]
	ds_read_b64_tr_b16 v[230:231], v159 offset:41984
	ds_read_b64_tr_b16 v[232:233], v159 offset:42496
	v_exp_f32_e32 v74, v74
	v_exp_f32_e32 v75, v75
	v_add_f32_e32 v157, v157, v74
	v_add_f32_e32 v157, v157, v75
	v_cvt_pk_bf16_f32 v69, v74, v75
	s_waitcnt lgkmcnt(15)
	v_mfma_f32_32x32x16_bf16 v[238:253], v[234:237], v[88:91], v[238:253]
	ds_read_b64_tr_b16 v[234:235], v159 offset:43008
	ds_read_b64_tr_b16 v[236:237], v159 offset:43520
	v_exp_f32_e32 v76, v76
	v_exp_f32_e32 v77, v77
	v_add_f32_e32 v156, v156, v76
	v_add_f32_e32 v156, v156, v77
	v_cvt_pk_bf16_f32 v70, v76, v77
	s_waitcnt lgkmcnt(15)
	v_mfma_f32_32x32x16_bf16 v[180:195], v[164:167], v[88:91], v[180:195]
	ds_read_b64_tr_b16 v[164:165], v159 offset:44032
	ds_read_b64_tr_b16 v[166:167], v159 offset:44544
	v_exp_f32_e32 v78, v78
	v_exp_f32_e32 v79, v79
	v_add_f32_e32 v157, v157, v78
	v_add_f32_e32 v157, v157, v79
	v_cvt_pk_bf16_f32 v71, v78, v79
	s_waitcnt lgkmcnt(15)
	v_mfma_f32_32x32x16_bf16 v[238:253], v[168:171], v[84:87], v[238:253]
	v_exp_f32_e32 v48, v48
	v_exp_f32_e32 v49, v49
	v_add_f32_e32 v156, v156, v48
	v_add_f32_e32 v156, v156, v49
	v_cvt_pk_bf16_f32 v48, v48, v49
	s_waitcnt lgkmcnt(15)
	v_mfma_f32_32x32x16_bf16 v[180:195], v[172:175], v[84:87], v[180:195]
	v_exp_f32_e32 v50, v50
	v_exp_f32_e32 v51, v51
	v_add_f32_e32 v157, v157, v50
	v_add_f32_e32 v157, v157, v51
	v_cvt_pk_bf16_f32 v49, v50, v51
	s_waitcnt lgkmcnt(15)
	v_mfma_f32_32x32x16_bf16 v[238:253], v[148:151], v[80:83], v[238:253]
	v_exp_f32_e32 v52, v52
	v_exp_f32_e32 v53, v53
	v_add_f32_e32 v156, v156, v52
	v_add_f32_e32 v156, v156, v53
	v_cvt_pk_bf16_f32 v50, v52, v53
	s_waitcnt lgkmcnt(15)
	v_mfma_f32_32x32x16_bf16 v[180:195], v[152:155], v[80:83], v[180:195]
	v_exp_f32_e32 v54, v54
	v_exp_f32_e32 v55, v55
	v_add_f32_e32 v157, v157, v54
	v_add_f32_e32 v157, v157, v55
	v_cvt_pk_bf16_f32 v51, v54, v55
	s_nop 1
	s_waitcnt lgkmcnt(14)
	v_mfma_f32_32x32x16_bf16 v[16:31], v[64:67], v[196:199], v[16:31]
	v_exp_f32_e32 v56, v56
	v_exp_f32_e32 v57, v57
	v_add_f32_e32 v156, v156, v56
	v_add_f32_e32 v156, v156, v57
	v_cvt_pk_bf16_f32 v52, v56, v57
	s_nop 1
	s_waitcnt lgkmcnt(6)
	v_mfma_f32_32x32x16_bf16 v[32:47], v[64:67], v[212:215], v[32:47]
	s_mul_i32 s53, s48, 0x3000
	s_add_i32 s4, s52, 2
	s_cmp_ge_u32 s4, s86
	s_cbranch_scc1 .Lat_u1x_nodma
	s_add_i32 s4, s53, 0xffffd000
	s_cmp_lg_u32 s48, 0
	s_cselect_b32 s4, s4, 0x6000
	s_add_i32 s5, s4, s97
	s_mov_b32 m0, s5
	s_add_i32 s4, s4, s72
	global_load_lds_dwordx4 v[126:127], off
	s_mov_b32 m0, s4
	s_lshl_b32 s5, s50, 13
	global_load_lds_dwordx4 v[14:15], off
	s_xor_b32 s5, s5, 0x4000
	s_add_i32 s5, s5, s73
	s_mov_b32 m0, s5
	s_nop 0
	global_load_lds_dwordx4 v[124:125], off
; __device__ __forceinline__ void cmask(f32x16& p0, f32x16& p1, int jb, int qrel, int hi) {
;     const float NEG = -INFINITY; const int kb = 64 * jb + 4 * hi;
; #pragma unroll
;     for (int r = 0; r < 16; ++r) { const int kv = kb + (r & 3) + 8 * (r >> 2); if (kv > qrel) p0[r] = NEG; if (kv + 32 > qrel) p1[r] = NEG; }
; }
.Lat_u1x_nodma:
	v_lshl_add_u64 v[126:127], v[126:127], 0, s[34:35]
	v_lshl_add_u64 v[14:15], v[14:15], 0, s[20:21]
	v_lshl_add_u64 v[124:125], v[124:125], 0, s[34:35]
	v_exp_f32_e32 v58, v58
	v_exp_f32_e32 v59, v59
	v_add_f32_e32 v157, v157, v58
	v_add_f32_e32 v157, v157, v59
	v_cvt_pk_bf16_f32 v53, v58, v59
	s_nop 1
	s_waitcnt lgkmcnt(12)
	v_mfma_f32_32x32x16_bf16 v[16:31], v[68:71], v[200:203], v[16:31]
	v_exp_f32_e32 v60, v60
	v_exp_f32_e32 v61, v61
	v_add_f32_e32 v156, v156, v60
	v_add_f32_e32 v156, v156, v61
	v_cvt_pk_bf16_f32 v54, v60, v61
	s_nop 1
	s_waitcnt lgkmcnt(4)
	v_mfma_f32_32x32x16_bf16 v[32:47], v[68:71], v[230:233], v[32:47]
	v_exp_f32_e32 v62, v62
	v_exp_f32_e32 v63, v63
	v_add_f32_e32 v157, v157, v62
	v_add_f32_e32 v157, v157, v63
	v_cvt_pk_bf16_f32 v55, v62, v63
	s_nop 1
	s_waitcnt lgkmcnt(10)
	v_mfma_f32_32x32x16_bf16 v[16:31], v[48:51], v[204:207], v[16:31]
	s_waitcnt lgkmcnt(2)
	v_mfma_f32_32x32x16_bf16 v[32:47], v[48:51], v[234:237], v[32:47]
	s_waitcnt lgkmcnt(8)
	v_mfma_f32_32x32x16_bf16 v[16:31], v[52:55], v[208:211], v[16:31]
	s_waitcnt lgkmcnt(0)
	v_mfma_f32_32x32x16_bf16 v[32:47], v[52:55], v[164:167], v[32:47]
	v_add_f32_e32 v156, v156, v157
	v_add_f32_e32 v128, v128, v156
	s_cmp_lt_u32 s52, s87
	s_cbranch_scc1 .Lat_u1x_nomask
	s_sub_i32 s4, s52, s87
	s_lshl_b32 s4, s4, 6
	s_nop 7
	s_nop 7
	v_lshl_add_u32 v147, v141, 2, s4
	v_sub_u32_e32 v147, v145, v147
	v_cmp_gt_i32_e32 vcc, 0, v147
	s_nop 1
	v_cndmask_b32_e32 v238, v238, v220, vcc
	v_cmp_gt_i32_e32 vcc, 1, v147
	s_nop 1
	v_cndmask_b32_e32 v239, v239, v220, vcc
	v_cmp_gt_i32_e32 vcc, 2, v147
	s_nop 1
	v_cndmask_b32_e32 v240, v240, v220, vcc
	v_cmp_gt_i32_e32 vcc, 3, v147
	s_nop 1
	v_cndmask_b32_e32 v241, v241, v220, vcc
	v_cmp_gt_i32_e32 vcc, 8, v147
	s_nop 1
	v_cndmask_b32_e32 v242, v242, v220, vcc
	v_cmp_gt_i32_e32 vcc, 9, v147
	s_nop 1
	v_cndmask_b32_e32 v243, v243, v220, vcc
	v_cmp_gt_i32_e32 vcc, 10, v147
	s_nop 1
	v_cndmask_b32_e32 v244, v244, v220, vcc
	v_cmp_gt_i32_e32 vcc, 11, v147
	s_nop 1
	v_cndmask_b32_e32 v245, v245, v220, vcc
	v_cmp_gt_i32_e32 vcc, 16, v147
	s_nop 1
	v_cndmask_b32_e32 v246, v246, v220, vcc
	v_cmp_gt_i32_e32 vcc, 17, v147
	s_nop 1
	v_cndmask_b32_e32 v247, v247, v220, vcc
	v_cmp_gt_i32_e32 vcc, 18, v147
	s_nop 1
	v_cndmask_b32_e32 v248, v248, v220, vcc
	v_cmp_gt_i32_e32 vcc, 19, v147
	s_nop 1
	v_cndmask_b32_e32 v249, v249, v220, vcc
	v_cmp_gt_i32_e32 vcc, 24, v147
	s_nop 1
	v_cndmask_b32_e32 v250, v250, v220, vcc
	v_cmp_gt_i32_e32 vcc, 25, v147
	s_nop 1
	v_cndmask_b32_e32 v251, v251, v220, vcc
	v_cmp_gt_i32_e32 vcc, 26, v147
	s_nop 1
	v_cndmask_b32_e32 v252, v252, v220, vcc
	v_cmp_gt_i32_e32 vcc, 27, v147
	s_nop 1
	v_cndmask_b32_e32 v253, v253, v220, vcc
	v_cmp_gt_i32_e32 vcc, 32, v147
	s_nop 1
	v_cndmask_b32_e32 v180, v180, v220, vcc
	v_cmp_gt_i32_e32 vcc, 33, v147
	s_nop 1
	v_cndmask_b32_e32 v181, v181, v220, vcc
	v_cmp_gt_i32_e32 vcc, 34, v147
	s_nop 1
	v_cndmask_b32_e32 v182, v182, v220, vcc
	v_cmp_gt_i32_e32 vcc, 35, v147
	s_nop 1
	v_cndmask_b32_e32 v183, v183, v220, vcc
	v_cmp_gt_i32_e32 vcc, 40, v147
	s_nop 1
	v_cndmask_b32_e32 v184, v184, v220, vcc
	v_cmp_gt_i32_e32 vcc, 41, v147
	s_nop 1
	v_cndmask_b32_e32 v185, v185, v220, vcc
	v_cmp_gt_i32_e32 vcc, 42, v147
	s_nop 1
	v_cndmask_b32_e32 v186, v186, v220, vcc
	v_cmp_gt_i32_e32 vcc, 43, v147
	s_nop 1
	v_cndmask_b32_e32 v187, v187, v220, vcc
	v_cmp_gt_i32_e32 vcc, 48, v147
	s_nop 1
	v_cndmask_b32_e32 v188, v188, v220, vcc
	v_cmp_gt_i32_e32 vcc, 49, v147
	s_nop 1
	v_cndmask_b32_e32 v189, v189, v220, vcc
	v_cmp_gt_i32_e32 vcc, 50, v147
	s_nop 1
	v_cndmask_b32_e32 v190, v190, v220, vcc
	v_cmp_gt_i32_e32 vcc, 51, v147
	s_nop 1
	v_cndmask_b32_e32 v191, v191, v220, vcc
	v_cmp_gt_i32_e32 vcc, 56, v147
	s_nop 1
	v_cndmask_b32_e32 v192, v192, v220, vcc
	v_cmp_gt_i32_e32 vcc, 57, v147
	s_nop 1
	v_cndmask_b32_e32 v193, v193, v220, vcc
	v_cmp_gt_i32_e32 vcc, 58, v147
	s_nop 1
	v_cndmask_b32_e32 v194, v194, v220, vcc
	v_cmp_gt_i32_e32 vcc, 59, v147
	s_nop 1
	v_cndmask_b32_e32 v195, v195, v220, vcc
.Lat_u1x_nomask:
	v_max3_f32 v129, v238, v239, v240
	v_max3_f32 v131, v241, v242, v243
	v_max3_f32 v129, v129, v244, v245
	v_max3_f32 v131, v131, v246, v247
	v_max3_f32 v129, v129, v248, v249
	v_max3_f32 v131, v131, v250, v251
	v_max3_f32 v129, v129, v252, v253
	v_max3_f32 v131, v131, v180, v181
	v_max3_f32 v129, v129, v182, v183
	v_max3_f32 v131, v131, v184, v185
	v_max3_f32 v129, v129, v186, v187
	v_max3_f32 v131, v131, v188, v189
	v_max3_f32 v129, v129, v190, v191
	v_max3_f32 v131, v131, v192, v193
	v_max3_f32 v129, v129, v194, v195
	v_max_f32_e32 v129, v129, v131
	v_mov_b32_e32 v131, v129
	s_nop 1
	v_permlane32_swap_b32_e32 v129, v131
	s_nop 0
	v_max_f32_e32 v129, v129, v131
	s_nop 0
	v_cmp_lt_f32_e32 vcc, 0x41000000, v129
	s_cbranch_vccnz .Lat_u1x_rare
.Lat_u1x_back:
	s_add_i32 s52, s52, 1
	s_add_i32 s4, s48, 1
	s_cmp_lg_u32 s48, 2
	s_cselect_b32 s48, s4, 0
	s_add_i32 s50, s50, 1
	s_and_b32 s50, s50, 3
	s_cmp_eq_u32 s52, s86
	s_cbranch_scc1 .Lat_u1_tail
	s_add_i32 s4, s52, 1
	s_cmp_ge_u32 s4, s86
	s_cbranch_scc1 .Lat_u1y_lw
	s_waitcnt vmcnt(3) lgkmcnt(0)
	s_branch .Lat_u1y_bar

.Lat_u1y_bar:
	s_barrier
	s_mul_i32 s53, s48, 0x3000
	v_add_u32_e32 v158, s53, v146
	ds_read_b128 v[196:199], v158
	ds_read_b128 v[200:203], v158 offset:512
	ds_read_b128 v[204:207], v158 offset:2048
	ds_read_b128 v[208:211], v158 offset:2560
	ds_read_b128 v[212:215], v158 offset:4096
	ds_read_b128 v[230:233], v158 offset:4608
	ds_read_b128 v[234:237], v158 offset:6144
	ds_read_b128 v[164:167], v158 offset:6656
	ds_read_b128 v[168:171], v158 offset:8192
	ds_read_b128 v[172:175], v158 offset:8704
	ds_read_b128 v[148:151], v158 offset:10240
	ds_read_b128 v[152:155], v158 offset:10752
	s_lshl_b32 s4, s50, 13
	s_add_i32 s4, s4, 0x6000
	s_and_b32 s4, s4, 0x6000
	v_add_u32_e32 v159, s4, v144
	v_mov_b32_e32 v156, 0
	v_mov_b32_e32 v157, 0
	s_waitcnt lgkmcnt(11)
	v_mfma_f32_32x32x16_bf16 v[64:79], v[196:199], v[100:103], v[104:119]
	ds_read_b64_tr_b16 v[196:197], v159 offset:36864
	ds_read_b64_tr_b16 v[198:199], v159 offset:37376
	v_exp_f32_e32 v238, v238
	v_exp_f32_e32 v239, v239
	v_add_f32_e32 v156, v156, v238
	v_add_f32_e32 v156, v156, v239
	v_cvt_pk_bf16_f32 v238, v238, v239
	s_waitcnt lgkmcnt(12)
	v_mfma_f32_32x32x16_bf16 v[48:63], v[200:203], v[100:103], v[104:119]
	ds_read_b64_tr_b16 v[200:201], v159 offset:37888
	ds_read_b64_tr_b16 v[202:203], v159 offset:38400
	v_exp_f32_e32 v240, v240
	v_exp_f32_e32 v241, v241
	v_add_f32_e32 v157, v157, v240
	v_add_f32_e32 v157, v157, v241
	v_cvt_pk_bf16_f32 v239, v240, v241
	s_waitcnt lgkmcnt(13)
	v_mfma_f32_32x32x16_bf16 v[64:79], v[204:207], v[96:99], v[64:79]
	ds_read_b64_tr_b16 v[204:205], v159 offset:38912
	ds_read_b64_tr_b16 v[206:207], v159 offset:39424
	v_exp_f32_e32 v242, v242
	v_exp_f32_e32 v243, v243
	v_add_f32_e32 v156, v156, v242
	v_add_f32_e32 v156, v156, v243
	v_cvt_pk_bf16_f32 v240, v242, v243
	s_waitcnt lgkmcnt(14)
	v_mfma_f32_32x32x16_bf16 v[48:63], v[208:211], v[96:99], v[48:63]
	ds_read_b64_tr_b16 v[208:209], v159 offset:39936
	ds_read_b64_tr_b16 v[210:211], v159 offset:40448
	v_exp_f32_e32 v244, v244
	v_exp_f32_e32 v245, v245
	v_add_f32_e32 v157, v157, v244
	v_add_f32_e32 v157, v157, v245
	v_cvt_pk_bf16_f32 v241, v244, v245
	s_waitcnt lgkmcnt(15)
	v_mfma_f32_32x32x16_bf16 v[64:79], v[212:215], v[92:95], v[64:79]
	ds_read_b64_tr_b16 v[212:213], v159 offset:40960
	ds_read_b64_tr_b16 v[214:215], v159 offset:41472
	v_exp_f32_e32 v246, v246
	v_exp_f32_e32 v247, v247
	v_add_f32_e32 v156, v156, v246
	v_add_f32_e32 v156, v156, v247
	v_cvt_pk_bf16_f32 v242, v246, v247
	s_waitcnt lgkmcnt(15)
	v_mfma_f32_32x32x16_bf16 v[48:63], v[230:233], v[92:95], v[48:63]
	ds_read_b64_tr_b16 v[230:231], v159 offset:41984
	ds_read_b64_tr_b16 v[232:233], v159 offset:42496
	v_exp_f32_e32 v248, v248
	v_exp_f32_e32 v249, v249
	v_add_f32_e32 v157, v157, v248
	v_add_f32_e32 v157, v157, v249
	v_cvt_pk_bf16_f32 v243, v248, v249
	s_waitcnt lgkmcnt(15)
	v_mfma_f32_32x32x16_bf16 v[64:79], v[234:237], v[88:91], v[64:79]
	ds_read_b64_tr_b16 v[234:235], v159 offset:43008
	ds_read_b64_tr_b16 v[236:237], v159 offset:43520
	v_exp_f32_e32 v250, v250
	v_exp_f32_e32 v251, v251
	v_add_f32_e32 v156, v156, v250
	v_add_f32_e32 v156, v156, v251
	v_cvt_pk_bf16_f32 v244, v250, v251
	s_waitcnt lgkmcnt(15)
	v_mfma_f32_32x32x16_bf16 v[48:63], v[164:167], v[88:91], v[48:63]
	ds_read_b64_tr_b16 v[164:165], v159 offset:44032
	ds_read_b64_tr_b16 v[166:167], v159 offset:44544
	v_exp_f32_e32 v252, v252
	v_exp_f32_e32 v253, v253
	v_add_f32_e32 v157, v157, v252
	v_add_f32_e32 v157, v157, v253
	v_cvt_pk_bf16_f32 v245, v252, v253
	s_waitcnt lgkmcnt(15)
	v_mfma_f32_32x32x16_bf16 v[64:79], v[168:171], v[84:87], v[64:79]
	v_exp_f32_e32 v180, v180
	v_exp_f32_e32 v181, v181
	v_add_f32_e32 v156, v156, v180
	v_add_f32_e32 v156, v156, v181
	v_cvt_pk_bf16_f32 v180, v180, v181
	s_waitcnt lgkmcnt(15)
	v_mfma_f32_32x32x16_bf16 v[48:63], v[172:175], v[84:87], v[48:63]
	v_exp_f32_e32 v182, v182
	v_exp_f32_e32 v183, v183
	v_add_f32_e32 v157, v157, v182
	v_add_f32_e32 v157, v157, v183
	v_cvt_pk_bf16_f32 v181, v182, v183
	s_waitcnt lgkmcnt(15)
	v_mfma_f32_32x32x16_bf16 v[64:79], v[148:151], v[80:83], v[64:79]
	v_exp_f32_e32 v184, v184
	v_exp_f32_e32 v185, v185
	v_add_f32_e32 v156, v156, v184
	v_add_f32_e32 v156, v156, v185
	v_cvt_pk_bf16_f32 v182, v184, v185
	s_waitcnt lgkmcnt(15)
	v_mfma_f32_32x32x16_bf16 v[48:63], v[152:155], v[80:83], v[48:63]
	v_exp_f32_e32 v186, v186
	v_exp_f32_e32 v187, v187
	v_add_f32_e32 v157, v157, v186
	v_add_f32_e32 v157, v157, v187
	v_cvt_pk_bf16_f32 v183, v186, v187
	s_nop 1
	s_waitcnt lgkmcnt(14)
	v_mfma_f32_32x32x16_bf16 v[16:31], v[238:241], v[196:199], v[16:31]
	v_exp_f32_e32 v188, v188
	v_exp_f32_e32 v189, v189
	v_add_f32_e32 v156, v156, v188
	v_add_f32_e32 v156, v156, v189
	v_cvt_pk_bf16_f32 v184, v188, v189
	s_nop 1
	s_waitcnt lgkmcnt(6)
	v_mfma_f32_32x32x16_bf16 v[32:47], v[238:241], v[212:215], v[32:47]
	s_mul_i32 s53, s48, 0x3000
	s_add_i32 s4, s52, 2
	s_cmp_ge_u32 s4, s86
	s_cbranch_scc1 .Lat_u1y_nodma
	s_add_i32 s4, s53, 0xffffd000
	s_cmp_lg_u32 s48, 0
	s_cselect_b32 s4, s4, 0x6000
	s_add_i32 s5, s4, s97
	s_mov_b32 m0, s5
	s_add_i32 s4, s4, s72
	global_load_lds_dwordx4 v[126:127], off
	s_mov_b32 m0, s4
	s_lshl_b32 s5, s50, 13
	global_load_lds_dwordx4 v[14:15], off
	s_xor_b32 s5, s5, 0x4000
	s_add_i32 s5, s5, s73
	s_mov_b32 m0, s5
	s_nop 0
	global_load_lds_dwordx4 v[124:125], off
; __device__ __forceinline__ void cmask(f32x16& p0, f32x16& p1, int jb, int qrel, int hi) {
;     const float NEG = -INFINITY; const int kb = 64 * jb + 4 * hi;
; #pragma unroll
;     for (int r = 0; r < 16; ++r) { const int kv = kb + (r & 3) + 8 * (r >> 2); if (kv > qrel) p0[r] = NEG; if (kv + 32 > qrel) p1[r] = NEG; }
; }
.Lat_u1y_nodma:
	v_lshl_add_u64 v[126:127], v[126:127], 0, s[34:35]
	v_lshl_add_u64 v[14:15], v[14:15], 0, s[20:21]
	v_lshl_add_u64 v[124:125], v[124:125], 0, s[34:35]
	v_exp_f32_e32 v190, v190
	v_exp_f32_e32 v191, v191
	v_add_f32_e32 v157, v157, v190
	v_add_f32_e32 v157, v157, v191
	v_cvt_pk_bf16_f32 v185, v190, v191
	s_nop 1
	s_waitcnt lgkmcnt(12)
	v_mfma_f32_32x32x16_bf16 v[16:31], v[242:245], v[200:203], v[16:31]
	v_exp_f32_e32 v192, v192
	v_exp_f32_e32 v193, v193
	v_add_f32_e32 v156, v156, v192
	v_add_f32_e32 v156, v156, v193
	v_cvt_pk_bf16_f32 v186, v192, v193
	s_nop 1
	s_waitcnt lgkmcnt(4)
	v_mfma_f32_32x32x16_bf16 v[32:47], v[242:245], v[230:233], v[32:47]
	v_exp_f32_e32 v194, v194
	v_exp_f32_e32 v195, v195
	v_add_f32_e32 v157, v157, v194
	v_add_f32_e32 v157, v157, v195
	v_cvt_pk_bf16_f32 v187, v194, v195
	s_nop 1
	s_waitcnt lgkmcnt(10)
	v_mfma_f32_32x32x16_bf16 v[16:31], v[180:183], v[204:207], v[16:31]
	s_waitcnt lgkmcnt(2)
	v_mfma_f32_32x32x16_bf16 v[32:47], v[180:183], v[234:237], v[32:47]
	s_waitcnt lgkmcnt(8)
	v_mfma_f32_32x32x16_bf16 v[16:31], v[184:187], v[208:211], v[16:31]
	s_waitcnt lgkmcnt(0)
	v_mfma_f32_32x32x16_bf16 v[32:47], v[184:187], v[164:167], v[32:47]
	v_add_f32_e32 v156, v156, v157
	v_add_f32_e32 v128, v128, v156
	s_cmp_lt_u32 s52, s87
	s_cbranch_scc1 .Lat_u1y_nomask
	s_sub_i32 s4, s52, s87
	s_lshl_b32 s4, s4, 6
	s_nop 7
	s_nop 7
	v_lshl_add_u32 v147, v141, 2, s4
	v_sub_u32_e32 v147, v145, v147
	v_cmp_gt_i32_e32 vcc, 0, v147
	s_nop 1
	v_cndmask_b32_e32 v64, v64, v220, vcc
	v_cmp_gt_i32_e32 vcc, 1, v147
	s_nop 1
	v_cndmask_b32_e32 v65, v65, v220, vcc
	v_cmp_gt_i32_e32 vcc, 2, v147
	s_nop 1
	v_cndmask_b32_e32 v66, v66, v220, vcc
	v_cmp_gt_i32_e32 vcc, 3, v147
	s_nop 1
	v_cndmask_b32_e32 v67, v67, v220, vcc
	v_cmp_gt_i32_e32 vcc, 8, v147
	s_nop 1
	v_cndmask_b32_e32 v68, v68, v220, vcc
	v_cmp_gt_i32_e32 vcc, 9, v147
	s_nop 1
	v_cndmask_b32_e32 v69, v69, v220, vcc
	v_cmp_gt_i32_e32 vcc, 10, v147
	s_nop 1
	v_cndmask_b32_e32 v70, v70, v220, vcc
	v_cmp_gt_i32_e32 vcc, 11, v147
	s_nop 1
	v_cndmask_b32_e32 v71, v71, v220, vcc
	v_cmp_gt_i32_e32 vcc, 16, v147
	s_nop 1
	v_cndmask_b32_e32 v72, v72, v220, vcc
	v_cmp_gt_i32_e32 vcc, 17, v147
	s_nop 1
	v_cndmask_b32_e32 v73, v73, v220, vcc
	v_cmp_gt_i32_e32 vcc, 18, v147
	s_nop 1
	v_cndmask_b32_e32 v74, v74, v220, vcc
	v_cmp_gt_i32_e32 vcc, 19, v147
	s_nop 1
	v_cndmask_b32_e32 v75, v75, v220, vcc
	v_cmp_gt_i32_e32 vcc, 24, v147
	s_nop 1
	v_cndmask_b32_e32 v76, v76, v220, vcc
	v_cmp_gt_i32_e32 vcc, 25, v147
	s_nop 1
	v_cndmask_b32_e32 v77, v77, v220, vcc
	v_cmp_gt_i32_e32 vcc, 26, v147
	s_nop 1
	v_cndmask_b32_e32 v78, v78, v220, vcc
	v_cmp_gt_i32_e32 vcc, 27, v147
	s_nop 1
	v_cndmask_b32_e32 v79, v79, v220, vcc
	v_cmp_gt_i32_e32 vcc, 32, v147
	s_nop 1
	v_cndmask_b32_e32 v48, v48, v220, vcc
	v_cmp_gt_i32_e32 vcc, 33, v147
	s_nop 1
	v_cndmask_b32_e32 v49, v49, v220, vcc
	v_cmp_gt_i32_e32 vcc, 34, v147
	s_nop 1
	v_cndmask_b32_e32 v50, v50, v220, vcc
	v_cmp_gt_i32_e32 vcc, 35, v147
	s_nop 1
	v_cndmask_b32_e32 v51, v51, v220, vcc
	v_cmp_gt_i32_e32 vcc, 40, v147
	s_nop 1
	v_cndmask_b32_e32 v52, v52, v220, vcc
	v_cmp_gt_i32_e32 vcc, 41, v147
	s_nop 1
	v_cndmask_b32_e32 v53, v53, v220, vcc
	v_cmp_gt_i32_e32 vcc, 42, v147
	s_nop 1
	v_cndmask_b32_e32 v54, v54, v220, vcc
	v_cmp_gt_i32_e32 vcc, 43, v147
	s_nop 1
	v_cndmask_b32_e32 v55, v55, v220, vcc
	v_cmp_gt_i32_e32 vcc, 48, v147
	s_nop 1
	v_cndmask_b32_e32 v56, v56, v220, vcc
	v_cmp_gt_i32_e32 vcc, 49, v147
	s_nop 1
	v_cndmask_b32_e32 v57, v57, v220, vcc
	v_cmp_gt_i32_e32 vcc, 50, v147
	s_nop 1
	v_cndmask_b32_e32 v58, v58, v220, vcc
	v_cmp_gt_i32_e32 vcc, 51, v147
	s_nop 1
	v_cndmask_b32_e32 v59, v59, v220, vcc
	v_cmp_gt_i32_e32 vcc, 56, v147
	s_nop 1
	v_cndmask_b32_e32 v60, v60, v220, vcc
	v_cmp_gt_i32_e32 vcc, 57, v147
	s_nop 1
	v_cndmask_b32_e32 v61, v61, v220, vcc
	v_cmp_gt_i32_e32 vcc, 58, v147
	s_nop 1
	v_cndmask_b32_e32 v62, v62, v220, vcc
	v_cmp_gt_i32_e32 vcc, 59, v147
	s_nop 1
	v_cndmask_b32_e32 v63, v63, v220, vcc
.Lat_u1y_nomask:
	v_max3_f32 v129, v64, v65, v66
	v_max3_f32 v131, v67, v68, v69
	v_max3_f32 v129, v129, v70, v71
	v_max3_f32 v131, v131, v72, v73
	v_max3_f32 v129, v129, v74, v75
	v_max3_f32 v131, v131, v76, v77
	v_max3_f32 v129, v129, v78, v79
	v_max3_f32 v131, v131, v48, v49
	v_max3_f32 v129, v129, v50, v51
	v_max3_f32 v131, v131, v52, v53
	v_max3_f32 v129, v129, v54, v55
	v_max3_f32 v131, v131, v56, v57
	v_max3_f32 v129, v129, v58, v59
	v_max3_f32 v131, v131, v60, v61
	v_max3_f32 v129, v129, v62, v63
	v_max_f32_e32 v129, v129, v131
	v_mov_b32_e32 v131, v129
	s_nop 1
	v_permlane32_swap_b32_e32 v129, v131
	s_nop 0
	v_max_f32_e32 v129, v129, v131
	s_nop 0
	v_cmp_lt_f32_e32 vcc, 0x41000000, v129
	s_cbranch_vccnz .Lat_u1y_rare
.Lat_u1y_back:
	s_add_i32 s52, s52, 1
	s_add_i32 s4, s48, 1
	s_cmp_lg_u32 s48, 2
	s_cselect_b32 s48, s4, 0
	s_add_i32 s50, s50, 1
	s_and_b32 s50, s50, 3
	s_branch .Lat_u1_loop
; #define V_LOAD(vs) do { const LAS char* vp_ = vp0 + (vs) * VSLOT; \
;         _Pragma("unroll") for (int i_ = 0; i_ < 8; ++i_) { vlo[i_] = vtr(vp_ + ((i_ >> 2) * 4096 + (i_ & 3) * 1024)); vhi[i_] = vtr(vp_ + ((i_ >> 2) * 4096 + (i_ & 3) * 1024 + 512)); } SBAR(); } while (0)
; __device__ __forceinline__ void attn_unit(int b, int h, int qb, const bf16* Q, const bf16* __restrict__ Kn, const bf16* __restrict__ Kpe, const bf16* __restrict__ V, bf16* O, float* ASS, LAS char* shm) {
;     ...
;         V_LOAD((vs + 3) & 3);
;         SOFTMAX();
;         PV_MMA();
.Lat_u1_tail:
	s_waitcnt lgkmcnt(0)
	s_lshl_b32 s4, s50, 13
	s_add_i32 s4, s4, 0x6000
	s_and_b32 s4, s4, 0x6000
	v_add_u32_e32 v159, s4, v144
	ds_read_b64_tr_b16 v[196:197], v159 offset:36864
	ds_read_b64_tr_b16 v[198:199], v159 offset:37376
	ds_read_b64_tr_b16 v[200:201], v159 offset:37888
	ds_read_b64_tr_b16 v[202:203], v159 offset:38400
	ds_read_b64_tr_b16 v[204:205], v159 offset:38912
	ds_read_b64_tr_b16 v[206:207], v159 offset:39424
	ds_read_b64_tr_b16 v[208:209], v159 offset:39936
	ds_read_b64_tr_b16 v[210:211], v159 offset:40448
	ds_read_b64_tr_b16 v[212:213], v159 offset:40960
	ds_read_b64_tr_b16 v[214:215], v159 offset:41472
	ds_read_b64_tr_b16 v[230:231], v159 offset:41984
	ds_read_b64_tr_b16 v[232:233], v159 offset:42496
	ds_read_b64_tr_b16 v[234:235], v159 offset:43008
	ds_read_b64_tr_b16 v[236:237], v159 offset:43520
	ds_read_b64_tr_b16 v[164:165], v159 offset:44032
	ds_read_b64_tr_b16 v[166:167], v159 offset:44544
	v_mov_b32_e32 v156, 0
	v_mov_b32_e32 v157, 0
	v_exp_f32_e32 v238, v238
	v_exp_f32_e32 v239, v239
	v_add_f32_e32 v156, v156, v238
	v_add_f32_e32 v156, v156, v239
	v_cvt_pk_bf16_f32 v238, v238, v239
	v_exp_f32_e32 v240, v240
	v_exp_f32_e32 v241, v241
	v_add_f32_e32 v157, v157, v240
	v_add_f32_e32 v157, v157, v241
	v_cvt_pk_bf16_f32 v239, v240, v241
	v_exp_f32_e32 v242, v242
	v_exp_f32_e32 v243, v243
	v_add_f32_e32 v156, v156, v242
	v_add_f32_e32 v156, v156, v243
	v_cvt_pk_bf16_f32 v240, v242, v243
	v_exp_f32_e32 v244, v244
	v_exp_f32_e32 v245, v245
	v_add_f32_e32 v157, v157, v244
	v_add_f32_e32 v157, v157, v245
	v_cvt_pk_bf16_f32 v241, v244, v245
	v_exp_f32_e32 v246, v246
	v_exp_f32_e32 v247, v247
	v_add_f32_e32 v156, v156, v246
	v_add_f32_e32 v156, v156, v247
	v_cvt_pk_bf16_f32 v242, v246, v247
	v_exp_f32_e32 v248, v248
	v_exp_f32_e32 v249, v249
	v_add_f32_e32 v157, v157, v248
	v_add_f32_e32 v157, v157, v249
	v_cvt_pk_bf16_f32 v243, v248, v249
	v_exp_f32_e32 v250, v250
	v_exp_f32_e32 v251, v251
	v_add_f32_e32 v156, v156, v250
	v_add_f32_e32 v156, v156, v251
	v_cvt_pk_bf16_f32 v244, v250, v251
	v_exp_f32_e32 v252, v252
	v_exp_f32_e32 v253, v253
	v_add_f32_e32 v157, v157, v252
	v_add_f32_e32 v157, v157, v253
	v_cvt_pk_bf16_f32 v245, v252, v253
	v_exp_f32_e32 v180, v180
	v_exp_f32_e32 v181, v181
	v_add_f32_e32 v156, v156, v180
	v_add_f32_e32 v156, v156, v181
	v_cvt_pk_bf16_f32 v180, v180, v181
	v_exp_f32_e32 v182, v182
	v_exp_f32_e32 v183, v183
	v_add_f32_e32 v157, v157, v182
	v_add_f32_e32 v157, v157, v183
	v_cvt_pk_bf16_f32 v181, v182, v183
	v_exp_f32_e32 v184, v184
	v_exp_f32_e32 v185, v185
	v_add_f32_e32 v156, v156, v184
	v_add_f32_e32 v156, v156, v185
	v_cvt_pk_bf16_f32 v182, v184, v185
	v_exp_f32_e32 v186, v186
	v_exp_f32_e32 v187, v187
	v_add_f32_e32 v157, v157, v186
	v_add_f32_e32 v157, v157, v187
	v_cvt_pk_bf16_f32 v183, v186, v187
	v_exp_f32_e32 v188, v188
	v_exp_f32_e32 v189, v189
	v_add_f32_e32 v156, v156, v188
	v_add_f32_e32 v156, v156, v189
	v_cvt_pk_bf16_f32 v184, v188, v189
	v_exp_f32_e32 v190, v190
	v_exp_f32_e32 v191, v191
	v_add_f32_e32 v157, v157, v190
	v_add_f32_e32 v157, v157, v191
	v_cvt_pk_bf16_f32 v185, v190, v191
	v_exp_f32_e32 v192, v192
	v_exp_f32_e32 v193, v193
	v_add_f32_e32 v156, v156, v192
	v_add_f32_e32 v156, v156, v193
	v_cvt_pk_bf16_f32 v186, v192, v193
	v_exp_f32_e32 v194, v194
	v_exp_f32_e32 v195, v195
	v_add_f32_e32 v157, v157, v194
	v_add_f32_e32 v157, v157, v195
	v_cvt_pk_bf16_f32 v187, v194, v195
	v_add_f32_e32 v156, v156, v157
	v_add_f32_e32 v128, v128, v156
	s_waitcnt lgkmcnt(0)
	v_mfma_f32_32x32x16_bf16 v[16:31], v[238:241], v[196:199], v[16:31]
	v_mfma_f32_32x32x16_bf16 v[32:47], v[238:241], v[212:215], v[32:47]
	v_mfma_f32_32x32x16_bf16 v[16:31], v[242:245], v[200:203], v[16:31]
	v_mfma_f32_32x32x16_bf16 v[32:47], v[242:245], v[230:233], v[32:47]
	v_mfma_f32_32x32x16_bf16 v[16:31], v[180:183], v[204:207], v[16:31]
	v_mfma_f32_32x32x16_bf16 v[32:47], v[180:183], v[234:237], v[32:47]
	v_mfma_f32_32x32x16_bf16 v[16:31], v[184:187], v[208:211], v[16:31]
	v_mfma_f32_32x32x16_bf16 v[32:47], v[184:187], v[164:167], v[32:47]
	s_mov_b32 m0, s54
	v_mov_b32_e32 v14, v128
	s_mov_b64 s[46:47], 0
	s_branch .LBB0_889
.Lat_u1x_rare:
	s_nop 15
	v_max_f32_e32 v131, 0, v129
	v_exp_f32_e64 v147, -v131
	v_add_f32_e32 v130, v130, v131
	s_nop 0
	s_and_saveexec_b64 s[46:47], s[38:39]
	ds_write_b32 v142, v147
	s_or_b64 exec, exec, s[46:47]
	v_mul_f32_e32 v128, v128, v147
	v_sub_f32_e32 v104, v104, v131
	v_sub_f32_e32 v105, v105, v131
	v_sub_f32_e32 v106, v106, v131
	v_sub_f32_e32 v107, v107, v131
	v_sub_f32_e32 v108, v108, v131
	v_sub_f32_e32 v109, v109, v131
	v_sub_f32_e32 v110, v110, v131
	v_sub_f32_e32 v111, v111, v131
	v_sub_f32_e32 v112, v112, v131
	v_sub_f32_e32 v113, v113, v131
	v_sub_f32_e32 v114, v114, v131
	v_sub_f32_e32 v115, v115, v131
	v_sub_f32_e32 v116, v116, v131
	v_sub_f32_e32 v117, v117, v131
	v_sub_f32_e32 v118, v118, v131
	v_sub_f32_e32 v119, v119, v131
	v_sub_f32_e32 v238, v238, v131
	v_sub_f32_e32 v239, v239, v131
	v_sub_f32_e32 v240, v240, v131
	v_sub_f32_e32 v241, v241, v131
	v_sub_f32_e32 v242, v242, v131
	v_sub_f32_e32 v243, v243, v131
	v_sub_f32_e32 v244, v244, v131
	v_sub_f32_e32 v245, v245, v131
	v_sub_f32_e32 v246, v246, v131
	v_sub_f32_e32 v247, v247, v131
	v_sub_f32_e32 v248, v248, v131
	v_sub_f32_e32 v249, v249, v131
	v_sub_f32_e32 v250, v250, v131
	v_sub_f32_e32 v251, v251, v131
	v_sub_f32_e32 v252, v252, v131
	v_sub_f32_e32 v253, v253, v131
	v_sub_f32_e32 v180, v180, v131
	v_sub_f32_e32 v181, v181, v131
	v_sub_f32_e32 v182, v182, v131
	v_sub_f32_e32 v183, v183, v131
	v_sub_f32_e32 v184, v184, v131
	v_sub_f32_e32 v185, v185, v131
	v_sub_f32_e32 v186, v186, v131
	v_sub_f32_e32 v187, v187, v131
	v_sub_f32_e32 v188, v188, v131
	v_sub_f32_e32 v189, v189, v131
	v_sub_f32_e32 v190, v190, v131
	v_sub_f32_e32 v191, v191, v131
	v_sub_f32_e32 v192, v192, v131
	v_sub_f32_e32 v193, v193, v131
	v_sub_f32_e32 v194, v194, v131
	v_sub_f32_e32 v195, v195, v131
	s_waitcnt lgkmcnt(0)
	v_add_u32_e32 v147, s96, v143
	ds_read_b128 v[2:5], v147
	ds_read_b128 v[6:9], v147 offset:32
	ds_read_b128 v[10:13], v147 offset:64
	ds_read_b128 v[120:123], v147 offset:96
	s_waitcnt lgkmcnt(0)
	v_mul_f32_e32 v16, v16, v2
	v_mul_f32_e32 v32, v32, v2
	v_mul_f32_e32 v17, v17, v3
	v_mul_f32_e32 v33, v33, v3
	v_mul_f32_e32 v18, v18, v4
	v_mul_f32_e32 v34, v34, v4
	v_mul_f32_e32 v19, v19, v5
	v_mul_f32_e32 v35, v35, v5
	v_mul_f32_e32 v20, v20, v6
	v_mul_f32_e32 v36, v36, v6
	v_mul_f32_e32 v21, v21, v7
	v_mul_f32_e32 v37, v37, v7
	v_mul_f32_e32 v22, v22, v8
	v_mul_f32_e32 v38, v38, v8
	v_mul_f32_e32 v23, v23, v9
	v_mul_f32_e32 v39, v39, v9
	v_mul_f32_e32 v24, v24, v10
	v_mul_f32_e32 v40, v40, v10
	v_mul_f32_e32 v25, v25, v11
	v_mul_f32_e32 v41, v41, v11
	v_mul_f32_e32 v26, v26, v12
	v_mul_f32_e32 v42, v42, v12
	v_mul_f32_e32 v27, v27, v13
	v_mul_f32_e32 v43, v43, v13
	v_mul_f32_e32 v28, v28, v120
	v_mul_f32_e32 v44, v44, v120
	v_mul_f32_e32 v29, v29, v121
	v_mul_f32_e32 v45, v45, v121
	v_mul_f32_e32 v30, v30, v122
	v_mul_f32_e32 v46, v46, v122
	v_mul_f32_e32 v31, v31, v123
	v_mul_f32_e32 v47, v47, v123
	s_branch .Lat_u1x_back
.Lat_u1y_rare:
	s_nop 15
	v_max_f32_e32 v131, 0, v129
	v_exp_f32_e64 v147, -v131
	v_add_f32_e32 v130, v130, v131
	s_nop 0
	s_and_saveexec_b64 s[46:47], s[38:39]
	ds_write_b32 v142, v147
	s_or_b64 exec, exec, s[46:47]
	v_mul_f32_e32 v128, v128, v147
	v_sub_f32_e32 v104, v104, v131
	v_sub_f32_e32 v105, v105, v131
	v_sub_f32_e32 v106, v106, v131
	v_sub_f32_e32 v107, v107, v131
	v_sub_f32_e32 v108, v108, v131
	v_sub_f32_e32 v109, v109, v131
	v_sub_f32_e32 v110, v110, v131
	v_sub_f32_e32 v111, v111, v131
	v_sub_f32_e32 v112, v112, v131
	v_sub_f32_e32 v113, v113, v131
	v_sub_f32_e32 v114, v114, v131
	v_sub_f32_e32 v115, v115, v131
	v_sub_f32_e32 v116, v116, v131
	v_sub_f32_e32 v117, v117, v131
	v_sub_f32_e32 v118, v118, v131
	v_sub_f32_e32 v119, v119, v131
	v_sub_f32_e32 v64, v64, v131
	v_sub_f32_e32 v65, v65, v131
	v_sub_f32_e32 v66, v66, v131
	v_sub_f32_e32 v67, v67, v131
	v_sub_f32_e32 v68, v68, v131
	v_sub_f32_e32 v69, v69, v131
	v_sub_f32_e32 v70, v70, v131
	v_sub_f32_e32 v71, v71, v131
	v_sub_f32_e32 v72, v72, v131
	v_sub_f32_e32 v73, v73, v131
	v_sub_f32_e32 v74, v74, v131
	v_sub_f32_e32 v75, v75, v131
	v_sub_f32_e32 v76, v76, v131
	v_sub_f32_e32 v77, v77, v131
	v_sub_f32_e32 v78, v78, v131
	v_sub_f32_e32 v79, v79, v131
	v_sub_f32_e32 v48, v48, v131
	v_sub_f32_e32 v49, v49, v131
	v_sub_f32_e32 v50, v50, v131
	v_sub_f32_e32 v51, v51, v131
	v_sub_f32_e32 v52, v52, v131
	v_sub_f32_e32 v53, v53, v131
	v_sub_f32_e32 v54, v54, v131
	v_sub_f32_e32 v55, v55, v131
	v_sub_f32_e32 v56, v56, v131
	v_sub_f32_e32 v57, v57, v131
	v_sub_f32_e32 v58, v58, v131
	v_sub_f32_e32 v59, v59, v131
	v_sub_f32_e32 v60, v60, v131
	v_sub_f32_e32 v61, v61, v131
	v_sub_f32_e32 v62, v62, v131
	v_sub_f32_e32 v63, v63, v131
	s_waitcnt lgkmcnt(0)
	v_add_u32_e32 v147, s96, v143
	ds_read_b128 v[2:5], v147
	ds_read_b128 v[6:9], v147 offset:32
	ds_read_b128 v[10:13], v147 offset:64
	ds_read_b128 v[120:123], v147 offset:96
	s_waitcnt lgkmcnt(0)
	v_mul_f32_e32 v16, v16, v2
	v_mul_f32_e32 v32, v32, v2
	v_mul_f32_e32 v17, v17, v3
	v_mul_f32_e32 v33, v33, v3
	v_mul_f32_e32 v18, v18, v4
	v_mul_f32_e32 v34, v34, v4
	v_mul_f32_e32 v19, v19, v5
	v_mul_f32_e32 v35, v35, v5
	v_mul_f32_e32 v20, v20, v6
	v_mul_f32_e32 v36, v36, v6
	v_mul_f32_e32 v21, v21, v7
	v_mul_f32_e32 v37, v37, v7
	v_mul_f32_e32 v22, v22, v8
	v_mul_f32_e32 v38, v38, v8
	v_mul_f32_e32 v23, v23, v9
	v_mul_f32_e32 v39, v39, v9
	v_mul_f32_e32 v24, v24, v10
	v_mul_f32_e32 v40, v40, v10
	v_mul_f32_e32 v25, v25, v11
	v_mul_f32_e32 v41, v41, v11
	v_mul_f32_e32 v26, v26, v12
	v_mul_f32_e32 v42, v42, v12
	v_mul_f32_e32 v27, v27, v13
	v_mul_f32_e32 v43, v43, v13
	v_mul_f32_e32 v28, v28, v120
	v_mul_f32_e32 v44, v44, v120
	v_mul_f32_e32 v29, v29, v121
	v_mul_f32_e32 v45, v45, v121
	v_mul_f32_e32 v30, v30, v122
	v_mul_f32_e32 v46, v46, v122
	v_mul_f32_e32 v31, v31, v123
	v_mul_f32_e32 v47, v47, v123
	s_branch .Lat_u1y_back

; #define LAS __attribute__((address_space(3)))
; #define SBAR() __builtin_amdgcn_sched_barrier(0)
; #define WAIT_BAR(N) asm volatile("s_waitcnt vmcnt(" #N ") lgkmcnt(0)\n\ts_barrier" ::: "memory")
; __device__ __forceinline__ void attn_unit(int b, int h, int qb, const bf16* Q, const bf16* __restrict__ Kn, const bf16* __restrict__ Kpe, const bf16* __restrict__ V, bf16* O, float* ASS, LAS char* shm) {
;     int tid_ = threadIdx.x; asm volatile("" : "+v"(tid_));
;     const int tid = tid_, lane = tid & 63, r32 = lane & 31, hi = lane >> 5; const int wid = __builtin_amdgcn_readfirstlane(tid >> 6);
;     const long rowbase = (long)b * SEQ; const int q0 = qb * QB;
;     const bf16* Qw = Q + (rowbase + q0 + wid * QBLK) * QP + h * 96;
;     const unsigned lds0 = (unsigned)(uintptr_t)shm;
;     LAS float* wsf = (LAS float*)(shm + LDS_WS) + wid * 64;
;     const bf16* ksrc = Kn + (rowbase + lane) * KNP + h * 64 + wid * 8;
;     const bf16* k2src = Kpe + (rowbase + lane) * KPP + (wid & 3) * 8;
;     const bf16* vsrc = V + (rowbase + 16 * (wid & 3) + (lane >> 2)) * VP + h * 64 + (wid >> 2) * 32 + (lane & 3) * 8;
;     const unsigned kdst = lds0 + LDS_K + wid * 1024, k2dst = lds0 + LDS_K + (8 + (wid & 3)) * 1024, vdst = lds0 + LDS_V + wid * 1024;
;     ...
;     const int vb0 = (int)(lds0 + LDS_V) + ((lane >> 4) & 1) * 32 + (lane & 3) * 8 + (4 * hi + ((lane & 15) >> 2)) * 64;
;     const int NT = (q0 + QB) / KVBLK;
;     DMA_TILE(0, 0, 0); DMA_TILE(1, 1, 1);
;     bf16x8 qr[6];
; #pragma unroll
;     for (int d0 = 0; d0 < 6; ++d0) qr[d0] = *reinterpret_cast<const bf16x8*>(&Qw[(long)r32 * QP + d0 * 16 + hi * 8]);
;     asm volatile("" : "+v"(qr[0]), "+v"(qr[1]), "+v"(qr[2]), "+v"(qr[3]), "+v"(qr[4]), "+v"(qr[5]));
;     float m_run = -1e30f, l_run = 0.f; f32x16 o[2]; o[0] = f32x16{}; o[1] = f32x16{};
;     const int qrel = wid * QBLK + r32;
;     f32x16 p0, p1;
;     ...
;         for (int t = 0; t < NT; ++t) {
;             if (t + 1 < NT) { WAIT_BAR(3); } else { WAIT_BAR(0); }
;             if (t > 0) V_LOAD((vs + 3) & 3);
;             if (t + 2 < NT) DMA_TILE(t + 2, (ks == 0) ? 2 : ks - 1, (vs + 2) & 3);
;             SBAR();
;             if (t > 0) SOFTMAX();
;             K_LOAD(ks);
;             if (t > 0) PV_MMA();
;             QK_MMA(t);
.LBB0_915:
	s_or_b64 exec, exec, s[38:39]
	v_mov_b32_e32 v139, v163
	s_waitcnt lgkmcnt(0)
	s_barrier
	v_mov_b32_e32 v3, s43
	v_readfirstlane_b32 s4, v139
	s_ashr_i32 s56, s4, 6
	s_lshl_b32 s5, s56, 5
	s_ashr_i32 s38, s5, 31
	s_add_u32 s52, s88, s5
	s_addc_u32 s53, s89, s38
	s_mul_i32 s38, s53, 0x600
	s_mul_hi_u32 s39, s52, 0x600
	s_add_i32 s39, s39, s38
	s_mul_i32 s38, s52, 0x600
	v_and_b32_e32 v140, 63, v139
	s_add_u32 s38, s78, s38
	s_addc_u32 s39, s79, s39
	s_waitcnt lgkmcnt(0)
	v_or_b32_e32 v2, s42, v140
	s_add_u32 s38, s38, s64
	v_lshlrev_b64 v[4:5], 10, v[2:3]
	s_addc_u32 s39, s39, s65
	v_lshl_add_u64 v[4:5], s[0:1], 0, v[4:5]
	s_lshl_b32 s54, s56, 3
	v_lshl_add_u64 v[4:5], v[4:5], 0, s[48:49]
	s_ashr_i32 s55, s54, 31
	s_and_b32 s57, s56, 3
	v_lshl_add_u64 v[90:91], s[54:55], 1, v[4:5]
	s_lshl_b32 s54, s57, 4
	v_bfe_u32 v0, v139, 2, 4
	v_lshlrev_b64 v[4:5], 6, v[2:3]
	v_or_b32_e32 v0, s54, v0
	v_lshl_add_u64 v[4:5], s[18:19], 0, v[4:5]
	s_mov_b32 s55, s49
	v_or_b32_e32 v2, s42, v0
	v_lshl_add_u64 v[92:93], v[4:5], 0, s[54:55]
	v_lshlrev_b64 v[2:3], 10, v[2:3]
	s_ashr_i32 s54, s4, 3
	v_lshl_add_u64 v[2:3], s[40:41], 0, v[2:3]
	s_andn2_b32 s54, s54, 31
	v_lshl_add_u64 v[2:3], v[2:3], 0, s[48:49]
	s_ashr_i32 s55, s54, 31
	v_lshl_add_u64 v[2:3], s[54:55], 1, v[2:3]
	v_lshlrev_b32_e32 v0, 3, v139
	s_lshl_b32 s54, s56, 10
	s_lshl_b32 s55, s57, 10
	v_and_b32_e32 v4, 24, v0
	s_add_i32 s58, s54, 0
	s_bitset1_b32 s55, 13
	s_mov_b32 s57, m0
	s_mov_b32 m0, s58
	s_nop 0
	global_load_lds_dwordx4 v[90:91], off
	s_mov_b32 m0, s57
	v_lshlrev_b32_e32 v0, 1, v4
	s_add_i32 s59, s55, 0
	s_mov_b32 s57, m0
	s_mov_b32 m0, s59
	s_nop 0
	global_load_lds_dwordx4 v[92:93], off
	s_mov_b32 m0, s57
	v_and_b32_e32 v141, 31, v139
	v_lshl_add_u64 v[94:95], v[2:3], 0, v[0:1]
	s_add_i32 s60, s58, 0x9000
	s_mov_b32 s57, m0
	s_mov_b32 m0, s60
	s_nop 0
	global_load_lds_dwordx4 v[94:95], off
	s_mov_b32 m0, s57
	v_lshl_add_u64 v[2:3], v[90:91], 0, s[34:35]
	s_add_i32 s57, s54, s33
	s_mov_b32 s61, m0
	s_mov_b32 m0, s57
	s_nop 0
	global_load_lds_dwordx4 v[2:3], off
	s_mov_b32 m0, s61
	v_mul_u32_u24_e32 v0, 0x300, v141
	v_bfe_u32 v142, v139, 5, 1
	v_lshl_add_u64 v[2:3], v[92:93], 0, s[20:21]
	s_add_i32 s57, s55, s33
	s_mov_b32 s61, m0
	s_mov_b32 m0, s57
	s_nop 0
	global_load_lds_dwordx4 v[2:3], off
	s_mov_b32 m0, s61
	v_lshlrev_b32_e32 v0, 1, v0
	v_lshl_add_u64 v[2:3], v[94:95], 0, s[34:35]
	s_add_i32 s57, s58, 0xb000
	s_mov_b32 s61, m0
	s_mov_b32 m0, s57
	s_nop 0
	global_load_lds_dwordx4 v[2:3], off
	s_mov_b32 m0, s61
	v_lshl_or_b32 v0, v142, 4, v0
	global_load_dwordx4 v[66:69], v0, s[38:39] offset:160
	global_load_dwordx4 v[70:73], v0, s[38:39] offset:128
	global_load_dwordx4 v[74:77], v0, s[38:39] offset:96
	global_load_dwordx4 v[78:81], v0, s[38:39] offset:64
	global_load_dwordx4 v[82:85], v0, s[38:39] offset:32
	global_load_dwordx4 v[86:89], v0, s[38:39]
	s_and_b32 s4, s4, 0x3fffffc0
	v_lshlrev_b32_e32 v0, 1, v139
	s_lshl_b32 s4, s4, 2
	v_lshlrev_b32_e32 v2, 4, v139
	v_and_b32_e32 v0, 32, v0
	s_add_i32 s57, s4, 0
	v_lshlrev_b32_e32 v3, 8, v142
	v_and_b32_e32 v2, 0xc0, v2
	v_lshlrev_b32_e32 v5, 10, v142
	v_lshlrev_b32_e32 v6, 4, v141
	v_add3_u32 v0, 0, v0, v4
	s_add_i32 s57, s57, 0x11000
	s_mov_b64 s[38:39], -1
	v_lshlrev_b32_e32 v144, 2, v142
	v_add3_u32 v146, 0, v5, v6
	v_or_b32_e32 v145, s5, v141
	v_add3_u32 v143, v0, v3, v2
	v_lshl_add_u64 v[130:131], v[90:91], 0, s[2:3]
	v_lshl_add_u64 v[132:133], v[92:93], 0, s[22:23]
	s_cmp_lt_i32 s56, 4
	v_lshl_add_u64 v[134:135], v[94:95], 0, s[2:3]
	s_waitcnt vmcnt(0)
	s_waitcnt vmcnt(3) lgkmcnt(0)
	s_barrier
	s_add_i32 s4, 0, 0x6000
	v_lshl_add_u64 v[2:3], v[90:91], 0, s[2:3]
	s_add_i32 s54, s54, s4
	s_mov_b32 s5, m0
	s_mov_b32 m0, s54
	s_nop 0
	global_load_lds_dwordx4 v[2:3], off
	s_mov_b32 m0, s5
	v_lshl_add_u64 v[2:3], v[92:93], 0, s[22:23]
	s_add_i32 s55, s55, s4
	s_mov_b32 s4, m0
	s_mov_b32 m0, s55
	s_nop 0
	global_load_lds_dwordx4 v[2:3], off
	s_mov_b32 m0, s4
	v_lshl_add_u64 v[2:3], v[94:95], 0, s[2:3]
	s_add_i32 s4, s58, 0xd000
	s_mov_b32 s5, m0
	s_mov_b32 m0, s4
	s_nop 0
	global_load_lds_dwordx4 v[2:3], off
	s_mov_b32 m0, s5
	ds_read_b128 v[2:5], v146
	ds_read_b128 v[6:9], v146 offset:512
	ds_read_b128 v[10:13], v146 offset:2048
	ds_read_b128 v[14:17], v146 offset:2560
	ds_read_b128 v[18:21], v146 offset:4096
	ds_read_b128 v[22:25], v146 offset:4608
	ds_read_b128 v[26:29], v146 offset:6144
	ds_read_b128 v[30:33], v146 offset:6656
	ds_read_b128 v[96:99], v146 offset:8192
	ds_read_b128 v[100:103], v146 offset:8704
	ds_read_b128 v[104:107], v146 offset:10240
	ds_read_b128 v[108:111], v146 offset:10752
	s_waitcnt lgkmcnt(11)
	v_mfma_f32_32x32x16_bf16 v[50:65], v[2:5], v[86:89], 0
	s_andn2_b64 vcc, exec, s[44:45]
	s_waitcnt lgkmcnt(10)
	v_mfma_f32_32x32x16_bf16 v[34:49], v[6:9], v[86:89], 0
	s_waitcnt lgkmcnt(9)
	v_mfma_f32_32x32x16_bf16 v[50:65], v[10:13], v[82:85], v[50:65]
	s_waitcnt lgkmcnt(8)
	v_mfma_f32_32x32x16_bf16 v[34:49], v[14:17], v[82:85], v[34:49]
	s_waitcnt lgkmcnt(7)
	v_mfma_f32_32x32x16_bf16 v[50:65], v[18:21], v[78:81], v[50:65]
	s_waitcnt lgkmcnt(6)
	v_mfma_f32_32x32x16_bf16 v[34:49], v[22:25], v[78:81], v[34:49]
	s_waitcnt lgkmcnt(5)
	v_mfma_f32_32x32x16_bf16 v[50:65], v[26:29], v[74:77], v[50:65]
	s_waitcnt lgkmcnt(4)
	v_mfma_f32_32x32x16_bf16 v[34:49], v[30:33], v[74:77], v[34:49]
	s_waitcnt lgkmcnt(3)
	v_mfma_f32_32x32x16_bf16 v[50:65], v[96:99], v[70:73], v[50:65]
	s_waitcnt lgkmcnt(2)
	v_mfma_f32_32x32x16_bf16 v[34:49], v[100:103], v[70:73], v[34:49]
	s_waitcnt lgkmcnt(1)
	v_mfma_f32_32x32x16_bf16 v[50:65], v[104:107], v[66:69], v[50:65]
	s_waitcnt lgkmcnt(0)
	v_mfma_f32_32x32x16_bf16 v[34:49], v[108:111], v[66:69], v[34:49]
	s_cbranch_vccnz .LBB0_918
; __device__ __forceinline__ void cmask(f32x16& p0, f32x16& p1, int jb, int qrel, int hi) {
;     const float NEG = -INFINITY; const int kb = 64 * jb + 4 * hi;
; #pragma unroll
;     for (int r = 0; r < 16; ++r) { const int kv = kb + (r & 3) + 8 * (r >> 2); if (kv > qrel) p0[r] = NEG; if (kv + 32 > qrel) p1[r] = NEG; }
; }
	v_or_b32_e32 v0, 32, v144
	v_cmp_le_i32_e32 vcc, v0, v145
	v_or_b32_e32 v0, 33, v144
	s_nop 7
	v_cndmask_b32_e32 v34, v220, v34, vcc
	v_cmp_lt_i32_e32 vcc, v144, v145
	s_nop 1
	v_cndmask_b32_e32 v51, v220, v51, vcc
	v_cmp_le_i32_e32 vcc, v144, v145
	s_nop 1
	v_cndmask_b32_e32 v50, v220, v50, vcc
	v_cmp_le_i32_e32 vcc, v0, v145
	v_or_b32_e32 v0, 2, v144
	s_nop 0
	v_cndmask_b32_e32 v35, v220, v35, vcc
	v_cmp_le_i32_e32 vcc, v0, v145
	v_or_b32_e32 v0, 34, v144
	s_nop 0
	v_cndmask_b32_e32 v52, v220, v52, vcc
	v_cmp_le_i32_e32 vcc, v0, v145
	v_or_b32_e32 v0, 3, v144
	s_nop 0
	v_cndmask_b32_e32 v36, v220, v36, vcc
	v_cmp_le_i32_e32 vcc, v0, v145
	v_or_b32_e32 v0, 35, v144
	s_nop 0
	v_cndmask_b32_e32 v53, v220, v53, vcc
	v_cmp_le_i32_e32 vcc, v0, v145
	v_or_b32_e32 v0, 8, v144
	s_nop 0
	v_cndmask_b32_e32 v37, v220, v37, vcc
	v_cmp_le_i32_e32 vcc, v0, v145
	v_or_b32_e32 v0, 40, v144
	s_nop 0
	v_cndmask_b32_e32 v54, v220, v54, vcc
	v_cmp_le_i32_e32 vcc, v0, v145
	v_or_b32_e32 v0, 9, v144
	s_nop 0
	v_cndmask_b32_e32 v38, v220, v38, vcc
	v_cmp_le_i32_e32 vcc, v0, v145
	v_or_b32_e32 v0, 41, v144
	s_nop 0
	v_cndmask_b32_e32 v55, v220, v55, vcc
	v_cmp_le_i32_e32 vcc, v0, v145
	v_or_b32_e32 v0, 10, v144
	s_nop 0
	v_cndmask_b32_e32 v39, v220, v39, vcc
	v_cmp_le_i32_e32 vcc, v0, v145
	v_or_b32_e32 v0, 42, v144
	s_nop 0
	v_cndmask_b32_e32 v56, v220, v56, vcc
	v_cmp_le_i32_e32 vcc, v0, v145
	v_or_b32_e32 v0, 11, v144
	s_nop 0
	v_cndmask_b32_e32 v40, v220, v40, vcc
	v_cmp_le_i32_e32 vcc, v0, v145
	v_or_b32_e32 v0, 43, v144
	s_nop 0
	v_cndmask_b32_e32 v57, v220, v57, vcc
	v_cmp_le_i32_e32 vcc, v0, v145
	v_or_b32_e32 v0, 16, v144
	s_nop 0
	v_cndmask_b32_e32 v41, v220, v41, vcc
	v_cmp_le_i32_e32 vcc, v0, v145
	v_or_b32_e32 v0, 48, v144
	s_nop 0
	v_cndmask_b32_e32 v58, v220, v58, vcc
	v_cmp_le_i32_e32 vcc, v0, v145
	v_or_b32_e32 v0, 17, v144
	s_nop 0
	v_cndmask_b32_e32 v42, v220, v42, vcc
	v_cmp_le_i32_e32 vcc, v0, v145
	v_or_b32_e32 v0, 49, v144
	s_nop 0
	v_cndmask_b32_e32 v59, v220, v59, vcc
	v_cmp_le_i32_e32 vcc, v0, v145
	v_or_b32_e32 v0, 18, v144
	s_nop 0
	v_cndmask_b32_e32 v43, v220, v43, vcc
	v_cmp_le_i32_e32 vcc, v0, v145
	v_or_b32_e32 v0, 50, v144
	s_nop 0
	v_cndmask_b32_e32 v60, v220, v60, vcc
	v_cmp_le_i32_e32 vcc, v0, v145
	v_or_b32_e32 v0, 19, v144
	s_nop 0
	v_cndmask_b32_e32 v44, v220, v44, vcc
	v_cmp_le_i32_e32 vcc, v0, v145
	v_or_b32_e32 v0, 51, v144
	s_nop 0
	v_cndmask_b32_e32 v61, v220, v61, vcc
	v_cmp_le_i32_e32 vcc, v0, v145
	v_or_b32_e32 v0, 24, v144
	s_nop 0
	v_cndmask_b32_e32 v45, v220, v45, vcc
	v_cmp_le_i32_e32 vcc, v0, v145
	v_or_b32_e32 v0, 56, v144
	s_nop 0
	v_cndmask_b32_e32 v62, v220, v62, vcc
	v_cmp_le_i32_e32 vcc, v0, v145
	v_or_b32_e32 v0, 25, v144
	s_nop 0
	v_cndmask_b32_e32 v46, v220, v46, vcc
	v_cmp_le_i32_e32 vcc, v0, v145
	v_or_b32_e32 v0, 57, v144
	s_nop 0
	v_cndmask_b32_e32 v63, v220, v63, vcc
	v_cmp_le_i32_e32 vcc, v0, v145
	v_or_b32_e32 v0, 26, v144
	s_nop 0
	v_cndmask_b32_e32 v47, v220, v47, vcc
	v_cmp_le_i32_e32 vcc, v0, v145
	v_or_b32_e32 v0, 58, v144
	s_nop 0
	v_cndmask_b32_e32 v64, v220, v64, vcc
	v_cmp_le_i32_e32 vcc, v0, v145
	v_or_b32_e32 v0, 27, v144
	s_nop 0
	v_cndmask_b32_e32 v48, v220, v48, vcc
	v_cmp_le_i32_e32 vcc, v0, v145
	v_or_b32_e32 v0, 59, v144
	s_nop 0
	v_cndmask_b32_e32 v65, v220, v65, vcc
	v_cmp_le_i32_e32 vcc, v0, v145
	s_nop 1
	v_cndmask_b32_e32 v49, v220, v49, vcc
; __device__ __forceinline__ float max3f(float a, float b, float c) { return __builtin_fmaxf(__builtin_fmaxf(a, b), c); }
; __device__ __forceinline__ float rowmax(const f32x16& p0, const f32x16& p1) {
;     float a = max3f(p0[0], p0[1], p1[0]), b = max3f(p0[2], p0[3], p1[1]); a = max3f(a, p1[2], p1[3]);
; #pragma unroll
;     for (int r = 4; r < 16; r += 4) { a = max3f(a, p0[r], p0[r + 1]); b = max3f(b, p0[r + 2], p0[r + 3]); a = max3f(a, p1[r], p1[r + 1]); b = max3f(b, p1[r + 2], p1[r + 3]); }
;     const float m = __builtin_fmaxf(a, b);
;     auto rr = __builtin_amdgcn_permlane32_swap(__float_as_uint(m), __float_as_uint(m), false, false);
;     return __builtin_fmaxf(__uint_as_float(rr[0]), __uint_as_float(rr[1]));
; }
; __device__ __forceinline__ void attn_unit(int b, int h, int qb, const bf16* Q, const bf16* __restrict__ Kn, const bf16* __restrict__ Kpe, const bf16* __restrict__ V, bf16* O, float* ASS, LAS char* shm) {
;     ...
;     float m_run = -1e30f, l_run = 0.f; f32x16 o[2]; o[0] = f32x16{}; o[1] = f32x16{};
;     const int qrel = wid * QBLK + r32;
;     f32x16 p0, p1;
.LBB0_918:
	v_cmp_gt_u32_e64 s[38:39], 32, v140
	v_lshl_add_u32 v147, v141, 2, s57
	v_lshlrev_b32_e32 v129, 4, v142
	v_mov_b32_e32 v14, v1
	v_mov_b32_e32 v15, v1
	v_mov_b32_e32 v0, v1
	v_mov_b32_e32 v2, v1
	v_mov_b32_e32 v3, v1
	v_mov_b32_e32 v4, v1
	v_mov_b32_e32 v5, v1
	v_mov_b32_e32 v6, v1
	v_mov_b32_e32 v7, v1
	v_mov_b32_e32 v8, v1
	v_mov_b32_e32 v9, v1
	v_mov_b32_e32 v10, v1
	v_mov_b32_e32 v11, v1
	v_mov_b32_e32 v12, v1
	v_mov_b32_e32 v13, v1
	v_mov_b64_e32 v[32:33], v[14:15]
	s_mov_b64 s[4:5], 0x30000
	v_mov_b64_e32 v[30:31], v[12:13]
	v_mov_b64_e32 v[28:29], v[10:11]
	v_mov_b64_e32 v[26:27], v[8:9]
	v_mov_b64_e32 v[24:25], v[6:7]
	v_mov_b64_e32 v[22:23], v[4:5]
	v_mov_b64_e32 v[20:21], v[2:3]
	v_mov_b64_e32 v[18:19], v[0:1]
	v_mov_b64_e32 v[16:17], v[14:15]
	v_lshl_add_u64 v[122:123], v[92:93], 0, s[6:7]
	v_lshl_add_u64 v[124:125], v[94:95], 0, s[4:5]
	v_lshl_add_u64 v[126:127], v[90:91], 0, s[4:5]
	s_mov_b32 s61, 1
	v_mov_b32_e32 v128, 0
	v_mov_b32_e32 v148, 0xf149f2ca
	s_mov_b32 s62, 3
	s_mov_b32 s63, s95
	v_mov_b64_e32 v[14:15], v[12:13]
	v_mov_b64_e32 v[12:13], v[10:11]
	v_mov_b64_e32 v[10:11], v[8:9]
	v_mov_b64_e32 v[8:9], v[6:7]
	v_mov_b64_e32 v[6:7], v[4:5]
	v_mov_b64_e32 v[4:5], v[2:3]
	v_mov_b64_e32 v[2:3], v[0:1]
	s_mov_b32 s64, 1
	s_add_i32 s4, s62, -1
	s_cmp_ge_u32 s4, s90
	s_mov_b64 s[54:55], -1
	s_branch .Lat_u2_entry
.Lat_u2_entry:
	s_mov_b32 s62, 1
	v_mov_b32_e32 v130, v148
	s_mov_b32 s65, m0
	s_nop 7
	s_nop 7
	v_max3_f32 v131, v50, v51, v52
	v_max3_f32 v132, v53, v54, v55
	v_max3_f32 v131, v131, v56, v57
	v_max3_f32 v132, v132, v58, v59
	v_max3_f32 v131, v131, v60, v61
	v_max3_f32 v132, v132, v62, v63
	v_max3_f32 v131, v131, v64, v65
	v_max3_f32 v132, v132, v34, v35
	v_max3_f32 v131, v131, v36, v37
	v_max3_f32 v132, v132, v38, v39
	v_max3_f32 v131, v131, v40, v41
	v_max3_f32 v132, v132, v42, v43
	v_max3_f32 v131, v131, v44, v45
	v_max3_f32 v132, v132, v46, v47
	v_max3_f32 v131, v131, v48, v49
	v_max_f32_e32 v131, v131, v132
	v_mov_b32_e32 v132, v131
	s_nop 1
	v_permlane32_swap_b32_e32 v131, v132
	s_nop 0
	v_max_f32_e32 v131, v131, v132
	v_mov_b32_e32 v130, v131
	v_sub_f32_e32 v104, 0, v131
	v_sub_f32_e32 v105, 0, v131
	v_sub_f32_e32 v106, 0, v131
	v_sub_f32_e32 v107, 0, v131
	v_sub_f32_e32 v108, 0, v131
	v_sub_f32_e32 v109, 0, v131
	v_sub_f32_e32 v110, 0, v131
	v_sub_f32_e32 v111, 0, v131
	v_sub_f32_e32 v112, 0, v131
	v_sub_f32_e32 v113, 0, v131
	v_sub_f32_e32 v114, 0, v131
	v_sub_f32_e32 v115, 0, v131
	v_sub_f32_e32 v116, 0, v131
	v_sub_f32_e32 v117, 0, v131
	v_sub_f32_e32 v118, 0, v131
	v_sub_f32_e32 v119, 0, v131
	v_sub_f32_e32 v50, v50, v131
	v_sub_f32_e32 v51, v51, v131
	v_sub_f32_e32 v52, v52, v131
	v_sub_f32_e32 v53, v53, v131
	v_sub_f32_e32 v54, v54, v131
	v_sub_f32_e32 v55, v55, v131
	v_sub_f32_e32 v56, v56, v131
	v_sub_f32_e32 v57, v57, v131
	v_sub_f32_e32 v58, v58, v131
	v_sub_f32_e32 v59, v59, v131
	v_sub_f32_e32 v60, v60, v131
	v_sub_f32_e32 v61, v61, v131
	v_sub_f32_e32 v62, v62, v131
	v_sub_f32_e32 v63, v63, v131
	v_sub_f32_e32 v64, v64, v131
	v_sub_f32_e32 v65, v65, v131
	v_sub_f32_e32 v34, v34, v131
	v_sub_f32_e32 v35, v35, v131
	v_sub_f32_e32 v36, v36, v131
	v_sub_f32_e32 v37, v37, v131
	v_sub_f32_e32 v38, v38, v131
	v_sub_f32_e32 v39, v39, v131
	v_sub_f32_e32 v40, v40, v131
	v_sub_f32_e32 v41, v41, v131
	v_sub_f32_e32 v42, v42, v131
	v_sub_f32_e32 v43, v43, v131
	v_sub_f32_e32 v44, v44, v131
	v_sub_f32_e32 v45, v45, v131
	v_sub_f32_e32 v46, v46, v131
	v_sub_f32_e32 v47, v47, v131
	v_sub_f32_e32 v48, v48, v131
	v_sub_f32_e32 v49, v49, v131
.Lat_u2_loop:
	s_add_i32 s4, s62, 1
	s_cmp_ge_u32 s4, s90
	s_cbranch_scc1 .Lat_u2x_lw
	s_waitcnt vmcnt(3) lgkmcnt(0)
	s_branch .Lat_u2x_bar

.Lat_u2x_bar:
	s_barrier
	s_mul_i32 s63, s61, 0x3000
	v_add_u32_e32 v158, s63, v146
	ds_read_b128 v[196:199], v158
	ds_read_b128 v[200:203], v158 offset:512
	ds_read_b128 v[204:207], v158 offset:2048
	ds_read_b128 v[208:211], v158 offset:2560
	ds_read_b128 v[212:215], v158 offset:4096
	ds_read_b128 v[230:233], v158 offset:4608
	ds_read_b128 v[234:237], v158 offset:6144
	ds_read_b128 v[164:167], v158 offset:6656
	ds_read_b128 v[168:171], v158 offset:8192
	ds_read_b128 v[172:175], v158 offset:8704
	ds_read_b128 v[148:151], v158 offset:10240
	ds_read_b128 v[152:155], v158 offset:10752
	s_lshl_b32 s4, s64, 13
	s_add_i32 s4, s4, 0x6000
	s_and_b32 s4, s4, 0x6000
	v_add_u32_e32 v159, s4, v143
	v_mov_b32_e32 v156, 0
	v_mov_b32_e32 v157, 0
	s_waitcnt lgkmcnt(11)
	v_mfma_f32_32x32x16_bf16 v[238:253], v[196:199], v[86:89], v[104:119]
	ds_read_b64_tr_b16 v[196:197], v159 offset:36864
	ds_read_b64_tr_b16 v[198:199], v159 offset:37376
	v_exp_f32_e32 v50, v50
	v_exp_f32_e32 v51, v51
	v_add_f32_e32 v156, v156, v50
	v_add_f32_e32 v156, v156, v51
	v_cvt_pk_bf16_f32 v50, v50, v51
	s_waitcnt lgkmcnt(12)
	v_mfma_f32_32x32x16_bf16 v[180:195], v[200:203], v[86:89], v[104:119]
	ds_read_b64_tr_b16 v[200:201], v159 offset:37888
	ds_read_b64_tr_b16 v[202:203], v159 offset:38400
	v_exp_f32_e32 v52, v52
	v_exp_f32_e32 v53, v53
	v_add_f32_e32 v157, v157, v52
	v_add_f32_e32 v157, v157, v53
	v_cvt_pk_bf16_f32 v51, v52, v53
	s_waitcnt lgkmcnt(13)
	v_mfma_f32_32x32x16_bf16 v[238:253], v[204:207], v[82:85], v[238:253]
	ds_read_b64_tr_b16 v[204:205], v159 offset:38912
	ds_read_b64_tr_b16 v[206:207], v159 offset:39424
	v_exp_f32_e32 v54, v54
	v_exp_f32_e32 v55, v55
	v_add_f32_e32 v156, v156, v54
	v_add_f32_e32 v156, v156, v55
	v_cvt_pk_bf16_f32 v52, v54, v55
	s_waitcnt lgkmcnt(14)
	v_mfma_f32_32x32x16_bf16 v[180:195], v[208:211], v[82:85], v[180:195]
	ds_read_b64_tr_b16 v[208:209], v159 offset:39936
	ds_read_b64_tr_b16 v[210:211], v159 offset:40448
	v_exp_f32_e32 v56, v56
	v_exp_f32_e32 v57, v57
	v_add_f32_e32 v157, v157, v56
	v_add_f32_e32 v157, v157, v57
	v_cvt_pk_bf16_f32 v53, v56, v57
	s_waitcnt lgkmcnt(15)
	v_mfma_f32_32x32x16_bf16 v[238:253], v[212:215], v[78:81], v[238:253]
	ds_read_b64_tr_b16 v[212:213], v159 offset:40960
	ds_read_b64_tr_b16 v[214:215], v159 offset:41472
	v_exp_f32_e32 v58, v58
	v_exp_f32_e32 v59, v59
	v_add_f32_e32 v156, v156, v58
	v_add_f32_e32 v156, v156, v59
	v_cvt_pk_bf16_f32 v54, v58, v59
	s_waitcnt lgkmcnt(15)
	v_mfma_f32_32x32x16_bf16 v[180:195], v[230:233], v[78:81], v[180:195]
	ds_read_b64_tr_b16 v[230:231], v159 offset:41984
	ds_read_b64_tr_b16 v[232:233], v159 offset:42496
	v_exp_f32_e32 v60, v60
	v_exp_f32_e32 v61, v61
	v_add_f32_e32 v157, v157, v60
	v_add_f32_e32 v157, v157, v61
	v_cvt_pk_bf16_f32 v55, v60, v61
	s_waitcnt lgkmcnt(15)
	v_mfma_f32_32x32x16_bf16 v[238:253], v[234:237], v[74:77], v[238:253]
	ds_read_b64_tr_b16 v[234:235], v159 offset:43008
	ds_read_b64_tr_b16 v[236:237], v159 offset:43520
	v_exp_f32_e32 v62, v62
	v_exp_f32_e32 v63, v63
	v_add_f32_e32 v156, v156, v62
	v_add_f32_e32 v156, v156, v63
	v_cvt_pk_bf16_f32 v56, v62, v63
	s_waitcnt lgkmcnt(15)
	v_mfma_f32_32x32x16_bf16 v[180:195], v[164:167], v[74:77], v[180:195]
	ds_read_b64_tr_b16 v[164:165], v159 offset:44032
	ds_read_b64_tr_b16 v[166:167], v159 offset:44544
	v_exp_f32_e32 v64, v64
	v_exp_f32_e32 v65, v65
	v_add_f32_e32 v157, v157, v64
	v_add_f32_e32 v157, v157, v65
	v_cvt_pk_bf16_f32 v57, v64, v65
	s_waitcnt lgkmcnt(15)
	v_mfma_f32_32x32x16_bf16 v[238:253], v[168:171], v[70:73], v[238:253]
	v_exp_f32_e32 v34, v34
	v_exp_f32_e32 v35, v35
	v_add_f32_e32 v156, v156, v34
	v_add_f32_e32 v156, v156, v35
	v_cvt_pk_bf16_f32 v34, v34, v35
	s_waitcnt lgkmcnt(15)
	v_mfma_f32_32x32x16_bf16 v[180:195], v[172:175], v[70:73], v[180:195]
	v_exp_f32_e32 v36, v36
	v_exp_f32_e32 v37, v37
	v_add_f32_e32 v157, v157, v36
	v_add_f32_e32 v157, v157, v37
	v_cvt_pk_bf16_f32 v35, v36, v37
	s_waitcnt lgkmcnt(15)
	v_mfma_f32_32x32x16_bf16 v[238:253], v[148:151], v[66:69], v[238:253]
	v_exp_f32_e32 v38, v38
	v_exp_f32_e32 v39, v39
	v_add_f32_e32 v156, v156, v38
	v_add_f32_e32 v156, v156, v39
	v_cvt_pk_bf16_f32 v36, v38, v39
	s_waitcnt lgkmcnt(15)
	v_mfma_f32_32x32x16_bf16 v[180:195], v[152:155], v[66:69], v[180:195]
	v_exp_f32_e32 v40, v40
	v_exp_f32_e32 v41, v41
	v_add_f32_e32 v157, v157, v40
	v_add_f32_e32 v157, v157, v41
	v_cvt_pk_bf16_f32 v37, v40, v41
	s_nop 1
	s_waitcnt lgkmcnt(14)
	v_mfma_f32_32x32x16_bf16 v[18:33], v[50:53], v[196:199], v[18:33]
	v_exp_f32_e32 v42, v42
	v_exp_f32_e32 v43, v43
	v_add_f32_e32 v156, v156, v42
	v_add_f32_e32 v156, v156, v43
	v_cvt_pk_bf16_f32 v38, v42, v43
	s_nop 1
	s_waitcnt lgkmcnt(6)
	v_mfma_f32_32x32x16_bf16 v[2:17], v[50:53], v[212:215], v[2:17]
	s_mul_i32 s63, s61, 0x3000
	s_add_i32 s4, s62, 2
	s_cmp_ge_u32 s4, s90
	s_cbranch_scc1 .Lat_u2x_nodma
	s_add_i32 s4, s63, 0xffffd000
	s_cmp_lg_u32 s61, 0
	s_cselect_b32 s4, s4, 0x6000
	s_add_i32 s5, s4, s58
	s_mov_b32 m0, s5
	s_add_i32 s4, s4, s59
	global_load_lds_dwordx4 v[126:127], off
	s_mov_b32 m0, s4
	s_lshl_b32 s5, s64, 13
	global_load_lds_dwordx4 v[122:123], off
	s_xor_b32 s5, s5, 0x4000
	s_add_i32 s5, s5, s60
	s_mov_b32 m0, s5
	s_nop 0
	global_load_lds_dwordx4 v[124:125], off
; __device__ __forceinline__ void cmask(f32x16& p0, f32x16& p1, int jb, int qrel, int hi) {
;     const float NEG = -INFINITY; const int kb = 64 * jb + 4 * hi;
; #pragma unroll
;     for (int r = 0; r < 16; ++r) { const int kv = kb + (r & 3) + 8 * (r >> 2); if (kv > qrel) p0[r] = NEG; if (kv + 32 > qrel) p1[r] = NEG; }
; }
.Lat_u2x_nodma:
	v_lshl_add_u64 v[126:127], v[126:127], 0, s[34:35]
	v_lshl_add_u64 v[122:123], v[122:123], 0, s[20:21]
	v_lshl_add_u64 v[124:125], v[124:125], 0, s[34:35]
	v_exp_f32_e32 v44, v44
	v_exp_f32_e32 v45, v45
	v_add_f32_e32 v157, v157, v44
	v_add_f32_e32 v157, v157, v45
	v_cvt_pk_bf16_f32 v39, v44, v45
	s_nop 1
	s_waitcnt lgkmcnt(12)
	v_mfma_f32_32x32x16_bf16 v[18:33], v[54:57], v[200:203], v[18:33]
	v_exp_f32_e32 v46, v46
	v_exp_f32_e32 v47, v47
	v_add_f32_e32 v156, v156, v46
	v_add_f32_e32 v156, v156, v47
	v_cvt_pk_bf16_f32 v40, v46, v47
	s_nop 1
	s_waitcnt lgkmcnt(4)
	v_mfma_f32_32x32x16_bf16 v[2:17], v[54:57], v[230:233], v[2:17]
	v_exp_f32_e32 v48, v48
	v_exp_f32_e32 v49, v49
	v_add_f32_e32 v157, v157, v48
	v_add_f32_e32 v157, v157, v49
	v_cvt_pk_bf16_f32 v41, v48, v49
	s_nop 1
	s_waitcnt lgkmcnt(10)
	v_mfma_f32_32x32x16_bf16 v[18:33], v[34:37], v[204:207], v[18:33]
	s_waitcnt lgkmcnt(2)
	v_mfma_f32_32x32x16_bf16 v[2:17], v[34:37], v[234:237], v[2:17]
	s_waitcnt lgkmcnt(8)
	v_mfma_f32_32x32x16_bf16 v[18:33], v[38:41], v[208:211], v[18:33]
	s_waitcnt lgkmcnt(0)
	v_mfma_f32_32x32x16_bf16 v[2:17], v[38:41], v[164:167], v[2:17]
	v_add_f32_e32 v156, v156, v157
	v_add_f32_e32 v128, v128, v156
	s_cmp_lt_u32 s62, s91
	s_cbranch_scc1 .Lat_u2x_nomask
	s_sub_i32 s4, s62, s91
	s_lshl_b32 s4, s4, 6
	s_nop 7
	s_nop 7
	v_lshl_add_u32 v133, v142, 2, s4
	v_sub_u32_e32 v133, v145, v133
	v_cmp_gt_i32_e32 vcc, 0, v133
	s_nop 1
	v_cndmask_b32_e32 v238, v238, v220, vcc
	v_cmp_gt_i32_e32 vcc, 1, v133
	s_nop 1
	v_cndmask_b32_e32 v239, v239, v220, vcc
	v_cmp_gt_i32_e32 vcc, 2, v133
	s_nop 1
	v_cndmask_b32_e32 v240, v240, v220, vcc
	v_cmp_gt_i32_e32 vcc, 3, v133
	s_nop 1
	v_cndmask_b32_e32 v241, v241, v220, vcc
	v_cmp_gt_i32_e32 vcc, 8, v133
	s_nop 1
	v_cndmask_b32_e32 v242, v242, v220, vcc
	v_cmp_gt_i32_e32 vcc, 9, v133
	s_nop 1
	v_cndmask_b32_e32 v243, v243, v220, vcc
	v_cmp_gt_i32_e32 vcc, 10, v133
	s_nop 1
	v_cndmask_b32_e32 v244, v244, v220, vcc
	v_cmp_gt_i32_e32 vcc, 11, v133
	s_nop 1
	v_cndmask_b32_e32 v245, v245, v220, vcc
	v_cmp_gt_i32_e32 vcc, 16, v133
	s_nop 1
	v_cndmask_b32_e32 v246, v246, v220, vcc
	v_cmp_gt_i32_e32 vcc, 17, v133
	s_nop 1
	v_cndmask_b32_e32 v247, v247, v220, vcc
	v_cmp_gt_i32_e32 vcc, 18, v133
	s_nop 1
	v_cndmask_b32_e32 v248, v248, v220, vcc
	v_cmp_gt_i32_e32 vcc, 19, v133
	s_nop 1
	v_cndmask_b32_e32 v249, v249, v220, vcc
	v_cmp_gt_i32_e32 vcc, 24, v133
	s_nop 1
	v_cndmask_b32_e32 v250, v250, v220, vcc
	v_cmp_gt_i32_e32 vcc, 25, v133
	s_nop 1
	v_cndmask_b32_e32 v251, v251, v220, vcc
	v_cmp_gt_i32_e32 vcc, 26, v133
	s_nop 1
	v_cndmask_b32_e32 v252, v252, v220, vcc
	v_cmp_gt_i32_e32 vcc, 27, v133
	s_nop 1
	v_cndmask_b32_e32 v253, v253, v220, vcc
	v_cmp_gt_i32_e32 vcc, 32, v133
	s_nop 1
	v_cndmask_b32_e32 v180, v180, v220, vcc
	v_cmp_gt_i32_e32 vcc, 33, v133
	s_nop 1
	v_cndmask_b32_e32 v181, v181, v220, vcc
	v_cmp_gt_i32_e32 vcc, 34, v133
	s_nop 1
	v_cndmask_b32_e32 v182, v182, v220, vcc
	v_cmp_gt_i32_e32 vcc, 35, v133
	s_nop 1
	v_cndmask_b32_e32 v183, v183, v220, vcc
	v_cmp_gt_i32_e32 vcc, 40, v133
	s_nop 1
	v_cndmask_b32_e32 v184, v184, v220, vcc
	v_cmp_gt_i32_e32 vcc, 41, v133
	s_nop 1
	v_cndmask_b32_e32 v185, v185, v220, vcc
	v_cmp_gt_i32_e32 vcc, 42, v133
	s_nop 1
	v_cndmask_b32_e32 v186, v186, v220, vcc
	v_cmp_gt_i32_e32 vcc, 43, v133
	s_nop 1
	v_cndmask_b32_e32 v187, v187, v220, vcc
	v_cmp_gt_i32_e32 vcc, 48, v133
	s_nop 1
	v_cndmask_b32_e32 v188, v188, v220, vcc
	v_cmp_gt_i32_e32 vcc, 49, v133
	s_nop 1
	v_cndmask_b32_e32 v189, v189, v220, vcc
	v_cmp_gt_i32_e32 vcc, 50, v133
	s_nop 1
	v_cndmask_b32_e32 v190, v190, v220, vcc
	v_cmp_gt_i32_e32 vcc, 51, v133
	s_nop 1
	v_cndmask_b32_e32 v191, v191, v220, vcc
	v_cmp_gt_i32_e32 vcc, 56, v133
	s_nop 1
	v_cndmask_b32_e32 v192, v192, v220, vcc
	v_cmp_gt_i32_e32 vcc, 57, v133
	s_nop 1
	v_cndmask_b32_e32 v193, v193, v220, vcc
	v_cmp_gt_i32_e32 vcc, 58, v133
	s_nop 1
	v_cndmask_b32_e32 v194, v194, v220, vcc
	v_cmp_gt_i32_e32 vcc, 59, v133
	s_nop 1
	v_cndmask_b32_e32 v195, v195, v220, vcc
.Lat_u2x_nomask:
	v_max3_f32 v131, v238, v239, v240
	v_max3_f32 v132, v241, v242, v243
	v_max3_f32 v131, v131, v244, v245
	v_max3_f32 v132, v132, v246, v247
	v_max3_f32 v131, v131, v248, v249
	v_max3_f32 v132, v132, v250, v251
	v_max3_f32 v131, v131, v252, v253
	v_max3_f32 v132, v132, v180, v181
	v_max3_f32 v131, v131, v182, v183
	v_max3_f32 v132, v132, v184, v185
	v_max3_f32 v131, v131, v186, v187
	v_max3_f32 v132, v132, v188, v189
	v_max3_f32 v131, v131, v190, v191
	v_max3_f32 v132, v132, v192, v193
	v_max3_f32 v131, v131, v194, v195
	v_max_f32_e32 v131, v131, v132
	v_mov_b32_e32 v132, v131
	s_nop 1
	v_permlane32_swap_b32_e32 v131, v132
	s_nop 0
	v_max_f32_e32 v131, v131, v132
	s_nop 0
	v_cmp_lt_f32_e32 vcc, 0x41000000, v131
	s_cbranch_vccnz .Lat_u2x_rare
.Lat_u2x_back:
	s_add_i32 s62, s62, 1
	s_add_i32 s4, s61, 1
	s_cmp_lg_u32 s61, 2
	s_cselect_b32 s61, s4, 0
	s_add_i32 s64, s64, 1
	s_and_b32 s64, s64, 3
	s_cmp_eq_u32 s62, s90
	s_cbranch_scc1 .Lat_u2_tail
	s_add_i32 s4, s62, 1
	s_cmp_ge_u32 s4, s90
	s_cbranch_scc1 .Lat_u2y_lw
	s_waitcnt vmcnt(3) lgkmcnt(0)
	s_branch .Lat_u2y_bar

.Lat_u2y_bar:
	s_barrier
	s_mul_i32 s63, s61, 0x3000
	v_add_u32_e32 v158, s63, v146
	ds_read_b128 v[196:199], v158
	ds_read_b128 v[200:203], v158 offset:512
	ds_read_b128 v[204:207], v158 offset:2048
	ds_read_b128 v[208:211], v158 offset:2560
	ds_read_b128 v[212:215], v158 offset:4096
	ds_read_b128 v[230:233], v158 offset:4608
	ds_read_b128 v[234:237], v158 offset:6144
	ds_read_b128 v[164:167], v158 offset:6656
	ds_read_b128 v[168:171], v158 offset:8192
	ds_read_b128 v[172:175], v158 offset:8704
	ds_read_b128 v[148:151], v158 offset:10240
	ds_read_b128 v[152:155], v158 offset:10752
	s_lshl_b32 s4, s64, 13
	s_add_i32 s4, s4, 0x6000
	s_and_b32 s4, s4, 0x6000
	v_add_u32_e32 v159, s4, v143
	v_mov_b32_e32 v156, 0
	v_mov_b32_e32 v157, 0
	s_waitcnt lgkmcnt(11)
	v_mfma_f32_32x32x16_bf16 v[50:65], v[196:199], v[86:89], v[104:119]
	ds_read_b64_tr_b16 v[196:197], v159 offset:36864
	ds_read_b64_tr_b16 v[198:199], v159 offset:37376
	v_exp_f32_e32 v238, v238
	v_exp_f32_e32 v239, v239
	v_add_f32_e32 v156, v156, v238
	v_add_f32_e32 v156, v156, v239
	v_cvt_pk_bf16_f32 v238, v238, v239
	s_waitcnt lgkmcnt(12)
	v_mfma_f32_32x32x16_bf16 v[34:49], v[200:203], v[86:89], v[104:119]
	ds_read_b64_tr_b16 v[200:201], v159 offset:37888
	ds_read_b64_tr_b16 v[202:203], v159 offset:38400
	v_exp_f32_e32 v240, v240
	v_exp_f32_e32 v241, v241
	v_add_f32_e32 v157, v157, v240
	v_add_f32_e32 v157, v157, v241
	v_cvt_pk_bf16_f32 v239, v240, v241
	s_waitcnt lgkmcnt(13)
	v_mfma_f32_32x32x16_bf16 v[50:65], v[204:207], v[82:85], v[50:65]
	ds_read_b64_tr_b16 v[204:205], v159 offset:38912
	ds_read_b64_tr_b16 v[206:207], v159 offset:39424
	v_exp_f32_e32 v242, v242
	v_exp_f32_e32 v243, v243
	v_add_f32_e32 v156, v156, v242
	v_add_f32_e32 v156, v156, v243
	v_cvt_pk_bf16_f32 v240, v242, v243
	s_waitcnt lgkmcnt(14)
	v_mfma_f32_32x32x16_bf16 v[34:49], v[208:211], v[82:85], v[34:49]
	ds_read_b64_tr_b16 v[208:209], v159 offset:39936
	ds_read_b64_tr_b16 v[210:211], v159 offset:40448
	v_exp_f32_e32 v244, v244
	v_exp_f32_e32 v245, v245
	v_add_f32_e32 v157, v157, v244
	v_add_f32_e32 v157, v157, v245
	v_cvt_pk_bf16_f32 v241, v244, v245
	s_waitcnt lgkmcnt(15)
	v_mfma_f32_32x32x16_bf16 v[50:65], v[212:215], v[78:81], v[50:65]
	ds_read_b64_tr_b16 v[212:213], v159 offset:40960
	ds_read_b64_tr_b16 v[214:215], v159 offset:41472
	v_exp_f32_e32 v246, v246
	v_exp_f32_e32 v247, v247
	v_add_f32_e32 v156, v156, v246
	v_add_f32_e32 v156, v156, v247
	v_cvt_pk_bf16_f32 v242, v246, v247
	s_waitcnt lgkmcnt(15)
	v_mfma_f32_32x32x16_bf16 v[34:49], v[230:233], v[78:81], v[34:49]
	ds_read_b64_tr_b16 v[230:231], v159 offset:41984
	ds_read_b64_tr_b16 v[232:233], v159 offset:42496
	v_exp_f32_e32 v248, v248
	v_exp_f32_e32 v249, v249
	v_add_f32_e32 v157, v157, v248
	v_add_f32_e32 v157, v157, v249
	v_cvt_pk_bf16_f32 v243, v248, v249
	s_waitcnt lgkmcnt(15)
	v_mfma_f32_32x32x16_bf16 v[50:65], v[234:237], v[74:77], v[50:65]
	ds_read_b64_tr_b16 v[234:235], v159 offset:43008
	ds_read_b64_tr_b16 v[236:237], v159 offset:43520
	v_exp_f32_e32 v250, v250
	v_exp_f32_e32 v251, v251
	v_add_f32_e32 v156, v156, v250
	v_add_f32_e32 v156, v156, v251
	v_cvt_pk_bf16_f32 v244, v250, v251
	s_waitcnt lgkmcnt(15)
	v_mfma_f32_32x32x16_bf16 v[34:49], v[164:167], v[74:77], v[34:49]
	ds_read_b64_tr_b16 v[164:165], v159 offset:44032
	ds_read_b64_tr_b16 v[166:167], v159 offset:44544
	v_exp_f32_e32 v252, v252
	v_exp_f32_e32 v253, v253
	v_add_f32_e32 v157, v157, v252
	v_add_f32_e32 v157, v157, v253
	v_cvt_pk_bf16_f32 v245, v252, v253
	s_waitcnt lgkmcnt(15)
	v_mfma_f32_32x32x16_bf16 v[50:65], v[168:171], v[70:73], v[50:65]
	v_exp_f32_e32 v180, v180
	v_exp_f32_e32 v181, v181
	v_add_f32_e32 v156, v156, v180
	v_add_f32_e32 v156, v156, v181
	v_cvt_pk_bf16_f32 v180, v180, v181
	s_waitcnt lgkmcnt(15)
	v_mfma_f32_32x32x16_bf16 v[34:49], v[172:175], v[70:73], v[34:49]
	v_exp_f32_e32 v182, v182
	v_exp_f32_e32 v183, v183
	v_add_f32_e32 v157, v157, v182
	v_add_f32_e32 v157, v157, v183
	v_cvt_pk_bf16_f32 v181, v182, v183
	s_waitcnt lgkmcnt(15)
	v_mfma_f32_32x32x16_bf16 v[50:65], v[148:151], v[66:69], v[50:65]
	v_exp_f32_e32 v184, v184
	v_exp_f32_e32 v185, v185
	v_add_f32_e32 v156, v156, v184
	v_add_f32_e32 v156, v156, v185
	v_cvt_pk_bf16_f32 v182, v184, v185
	s_waitcnt lgkmcnt(15)
	v_mfma_f32_32x32x16_bf16 v[34:49], v[152:155], v[66:69], v[34:49]
	v_exp_f32_e32 v186, v186
	v_exp_f32_e32 v187, v187
	v_add_f32_e32 v157, v157, v186
	v_add_f32_e32 v157, v157, v187
	v_cvt_pk_bf16_f32 v183, v186, v187
	s_nop 1
	s_waitcnt lgkmcnt(14)
	v_mfma_f32_32x32x16_bf16 v[18:33], v[238:241], v[196:199], v[18:33]
	v_exp_f32_e32 v188, v188
	v_exp_f32_e32 v189, v189
	v_add_f32_e32 v156, v156, v188
	v_add_f32_e32 v156, v156, v189
	v_cvt_pk_bf16_f32 v184, v188, v189
	s_nop 1
	s_waitcnt lgkmcnt(6)
	v_mfma_f32_32x32x16_bf16 v[2:17], v[238:241], v[212:215], v[2:17]
	s_mul_i32 s63, s61, 0x3000
	s_add_i32 s4, s62, 2
	s_cmp_ge_u32 s4, s90
	s_cbranch_scc1 .Lat_u2y_nodma
	s_add_i32 s4, s63, 0xffffd000
	s_cmp_lg_u32 s61, 0
	s_cselect_b32 s4, s4, 0x6000
	s_add_i32 s5, s4, s58
	s_mov_b32 m0, s5
	s_add_i32 s4, s4, s59
	global_load_lds_dwordx4 v[126:127], off
	s_mov_b32 m0, s4
	s_lshl_b32 s5, s64, 13
	global_load_lds_dwordx4 v[122:123], off
	s_xor_b32 s5, s5, 0x4000
	s_add_i32 s5, s5, s60
	s_mov_b32 m0, s5
	s_nop 0
	global_load_lds_dwordx4 v[124:125], off
; __device__ __forceinline__ void cmask(f32x16& p0, f32x16& p1, int jb, int qrel, int hi) {
;     const float NEG = -INFINITY; const int kb = 64 * jb + 4 * hi;
; #pragma unroll
;     for (int r = 0; r < 16; ++r) { const int kv = kb + (r & 3) + 8 * (r >> 2); if (kv > qrel) p0[r] = NEG; if (kv + 32 > qrel) p1[r] = NEG; }
; }
.Lat_u2y_nodma:
	v_lshl_add_u64 v[126:127], v[126:127], 0, s[34:35]
	v_lshl_add_u64 v[122:123], v[122:123], 0, s[20:21]
	v_lshl_add_u64 v[124:125], v[124:125], 0, s[34:35]
	v_exp_f32_e32 v190, v190
	v_exp_f32_e32 v191, v191
	v_add_f32_e32 v157, v157, v190
	v_add_f32_e32 v157, v157, v191
	v_cvt_pk_bf16_f32 v185, v190, v191
	s_nop 1
	s_waitcnt lgkmcnt(12)
	v_mfma_f32_32x32x16_bf16 v[18:33], v[242:245], v[200:203], v[18:33]
	v_exp_f32_e32 v192, v192
	v_exp_f32_e32 v193, v193
	v_add_f32_e32 v156, v156, v192
	v_add_f32_e32 v156, v156, v193
	v_cvt_pk_bf16_f32 v186, v192, v193
	s_nop 1
	s_waitcnt lgkmcnt(4)
	v_mfma_f32_32x32x16_bf16 v[2:17], v[242:245], v[230:233], v[2:17]
	v_exp_f32_e32 v194, v194
	v_exp_f32_e32 v195, v195
	v_add_f32_e32 v157, v157, v194
	v_add_f32_e32 v157, v157, v195
	v_cvt_pk_bf16_f32 v187, v194, v195
	s_nop 1
	s_waitcnt lgkmcnt(10)
	v_mfma_f32_32x32x16_bf16 v[18:33], v[180:183], v[204:207], v[18:33]
	s_waitcnt lgkmcnt(2)
	v_mfma_f32_32x32x16_bf16 v[2:17], v[180:183], v[234:237], v[2:17]
	s_waitcnt lgkmcnt(8)
	v_mfma_f32_32x32x16_bf16 v[18:33], v[184:187], v[208:211], v[18:33]
	s_waitcnt lgkmcnt(0)
	v_mfma_f32_32x32x16_bf16 v[2:17], v[184:187], v[164:167], v[2:17]
	v_add_f32_e32 v156, v156, v157
	v_add_f32_e32 v128, v128, v156
	s_cmp_lt_u32 s62, s91
	s_cbranch_scc1 .Lat_u2y_nomask
	s_sub_i32 s4, s62, s91
	s_lshl_b32 s4, s4, 6
	s_nop 7
	s_nop 7
	v_lshl_add_u32 v133, v142, 2, s4
	v_sub_u32_e32 v133, v145, v133
	v_cmp_gt_i32_e32 vcc, 0, v133
	s_nop 1
	v_cndmask_b32_e32 v50, v50, v220, vcc
	v_cmp_gt_i32_e32 vcc, 1, v133
	s_nop 1
	v_cndmask_b32_e32 v51, v51, v220, vcc
	v_cmp_gt_i32_e32 vcc, 2, v133
	s_nop 1
	v_cndmask_b32_e32 v52, v52, v220, vcc
	v_cmp_gt_i32_e32 vcc, 3, v133
	s_nop 1
	v_cndmask_b32_e32 v53, v53, v220, vcc
	v_cmp_gt_i32_e32 vcc, 8, v133
	s_nop 1
	v_cndmask_b32_e32 v54, v54, v220, vcc
	v_cmp_gt_i32_e32 vcc, 9, v133
	s_nop 1
	v_cndmask_b32_e32 v55, v55, v220, vcc
	v_cmp_gt_i32_e32 vcc, 10, v133
	s_nop 1
	v_cndmask_b32_e32 v56, v56, v220, vcc
	v_cmp_gt_i32_e32 vcc, 11, v133
	s_nop 1
	v_cndmask_b32_e32 v57, v57, v220, vcc
	v_cmp_gt_i32_e32 vcc, 16, v133
	s_nop 1
	v_cndmask_b32_e32 v58, v58, v220, vcc
	v_cmp_gt_i32_e32 vcc, 17, v133
	s_nop 1
	v_cndmask_b32_e32 v59, v59, v220, vcc
	v_cmp_gt_i32_e32 vcc, 18, v133
	s_nop 1
	v_cndmask_b32_e32 v60, v60, v220, vcc
	v_cmp_gt_i32_e32 vcc, 19, v133
	s_nop 1
	v_cndmask_b32_e32 v61, v61, v220, vcc
	v_cmp_gt_i32_e32 vcc, 24, v133
	s_nop 1
	v_cndmask_b32_e32 v62, v62, v220, vcc
	v_cmp_gt_i32_e32 vcc, 25, v133
	s_nop 1
	v_cndmask_b32_e32 v63, v63, v220, vcc
	v_cmp_gt_i32_e32 vcc, 26, v133
	s_nop 1
	v_cndmask_b32_e32 v64, v64, v220, vcc
	v_cmp_gt_i32_e32 vcc, 27, v133
	s_nop 1
	v_cndmask_b32_e32 v65, v65, v220, vcc
	v_cmp_gt_i32_e32 vcc, 32, v133
	s_nop 1
	v_cndmask_b32_e32 v34, v34, v220, vcc
	v_cmp_gt_i32_e32 vcc, 33, v133
	s_nop 1
	v_cndmask_b32_e32 v35, v35, v220, vcc
	v_cmp_gt_i32_e32 vcc, 34, v133
	s_nop 1
	v_cndmask_b32_e32 v36, v36, v220, vcc
	v_cmp_gt_i32_e32 vcc, 35, v133
	s_nop 1
	v_cndmask_b32_e32 v37, v37, v220, vcc
	v_cmp_gt_i32_e32 vcc, 40, v133
	s_nop 1
	v_cndmask_b32_e32 v38, v38, v220, vcc
	v_cmp_gt_i32_e32 vcc, 41, v133
	s_nop 1
	v_cndmask_b32_e32 v39, v39, v220, vcc
	v_cmp_gt_i32_e32 vcc, 42, v133
	s_nop 1
	v_cndmask_b32_e32 v40, v40, v220, vcc
	v_cmp_gt_i32_e32 vcc, 43, v133
	s_nop 1
	v_cndmask_b32_e32 v41, v41, v220, vcc
	v_cmp_gt_i32_e32 vcc, 48, v133
	s_nop 1
	v_cndmask_b32_e32 v42, v42, v220, vcc
	v_cmp_gt_i32_e32 vcc, 49, v133
	s_nop 1
	v_cndmask_b32_e32 v43, v43, v220, vcc
	v_cmp_gt_i32_e32 vcc, 50, v133
	s_nop 1
	v_cndmask_b32_e32 v44, v44, v220, vcc
	v_cmp_gt_i32_e32 vcc, 51, v133
	s_nop 1
	v_cndmask_b32_e32 v45, v45, v220, vcc
	v_cmp_gt_i32_e32 vcc, 56, v133
	s_nop 1
	v_cndmask_b32_e32 v46, v46, v220, vcc
	v_cmp_gt_i32_e32 vcc, 57, v133
	s_nop 1
	v_cndmask_b32_e32 v47, v47, v220, vcc
	v_cmp_gt_i32_e32 vcc, 58, v133
	s_nop 1
	v_cndmask_b32_e32 v48, v48, v220, vcc
	v_cmp_gt_i32_e32 vcc, 59, v133
	s_nop 1
	v_cndmask_b32_e32 v49, v49, v220, vcc
.Lat_u2y_nomask:
	v_max3_f32 v131, v50, v51, v52
	v_max3_f32 v132, v53, v54, v55
	v_max3_f32 v131, v131, v56, v57
	v_max3_f32 v132, v132, v58, v59
	v_max3_f32 v131, v131, v60, v61
	v_max3_f32 v132, v132, v62, v63
	v_max3_f32 v131, v131, v64, v65
	v_max3_f32 v132, v132, v34, v35
	v_max3_f32 v131, v131, v36, v37
	v_max3_f32 v132, v132, v38, v39
	v_max3_f32 v131, v131, v40, v41
	v_max3_f32 v132, v132, v42, v43
	v_max3_f32 v131, v131, v44, v45
	v_max3_f32 v132, v132, v46, v47
	v_max3_f32 v131, v131, v48, v49
	v_max_f32_e32 v131, v131, v132
	v_mov_b32_e32 v132, v131
	s_nop 1
	v_permlane32_swap_b32_e32 v131, v132
	s_nop 0
	v_max_f32_e32 v131, v131, v132
	s_nop 0
	v_cmp_lt_f32_e32 vcc, 0x41000000, v131
	s_cbranch_vccnz .Lat_u2y_rare
.Lat_u2y_back:
	s_add_i32 s62, s62, 1
	s_add_i32 s4, s61, 1
	s_cmp_lg_u32 s61, 2
	s_cselect_b32 s61, s4, 0
	s_add_i32 s64, s64, 1
	s_and_b32 s64, s64, 3
	s_branch .Lat_u2_loop
; #define V_LOAD(vs) do { const LAS char* vp_ = vp0 + (vs) * VSLOT; \
;         _Pragma("unroll") for (int i_ = 0; i_ < 8; ++i_) { vlo[i_] = vtr(vp_ + ((i_ >> 2) * 4096 + (i_ & 3) * 1024)); vhi[i_] = vtr(vp_ + ((i_ >> 2) * 4096 + (i_ & 3) * 1024 + 512)); } SBAR(); } while (0)
; __device__ __forceinline__ void attn_unit(int b, int h, int qb, const bf16* Q, const bf16* __restrict__ Kn, const bf16* __restrict__ Kpe, const bf16* __restrict__ V, bf16* O, float* ASS, LAS char* shm) {
;     ...
;         V_LOAD((vs + 3) & 3);
;         SOFTMAX();
;         PV_MMA();
.Lat_u2_tail:
	s_waitcnt lgkmcnt(0)
	s_lshl_b32 s4, s64, 13
	s_add_i32 s4, s4, 0x6000
	s_and_b32 s4, s4, 0x6000
	v_add_u32_e32 v159, s4, v143
	ds_read_b64_tr_b16 v[196:197], v159 offset:36864
	ds_read_b64_tr_b16 v[198:199], v159 offset:37376
	ds_read_b64_tr_b16 v[200:201], v159 offset:37888
	ds_read_b64_tr_b16 v[202:203], v159 offset:38400
	ds_read_b64_tr_b16 v[204:205], v159 offset:38912
	ds_read_b64_tr_b16 v[206:207], v159 offset:39424
	ds_read_b64_tr_b16 v[208:209], v159 offset:39936
	ds_read_b64_tr_b16 v[210:211], v159 offset:40448
	ds_read_b64_tr_b16 v[212:213], v159 offset:40960
	ds_read_b64_tr_b16 v[214:215], v159 offset:41472
	ds_read_b64_tr_b16 v[230:231], v159 offset:41984
	ds_read_b64_tr_b16 v[232:233], v159 offset:42496
	ds_read_b64_tr_b16 v[234:235], v159 offset:43008
	ds_read_b64_tr_b16 v[236:237], v159 offset:43520
	ds_read_b64_tr_b16 v[164:165], v159 offset:44032
	ds_read_b64_tr_b16 v[166:167], v159 offset:44544
	v_mov_b32_e32 v156, 0
	v_mov_b32_e32 v157, 0
	v_exp_f32_e32 v238, v238
	v_exp_f32_e32 v239, v239
	v_add_f32_e32 v156, v156, v238
	v_add_f32_e32 v156, v156, v239
	v_cvt_pk_bf16_f32 v238, v238, v239
	v_exp_f32_e32 v240, v240
	v_exp_f32_e32 v241, v241
	v_add_f32_e32 v157, v157, v240
	v_add_f32_e32 v157, v157, v241
	v_cvt_pk_bf16_f32 v239, v240, v241
	v_exp_f32_e32 v242, v242
	v_exp_f32_e32 v243, v243
	v_add_f32_e32 v156, v156, v242
	v_add_f32_e32 v156, v156, v243
	v_cvt_pk_bf16_f32 v240, v242, v243
	v_exp_f32_e32 v244, v244
	v_exp_f32_e32 v245, v245
	v_add_f32_e32 v157, v157, v244
	v_add_f32_e32 v157, v157, v245
	v_cvt_pk_bf16_f32 v241, v244, v245
	v_exp_f32_e32 v246, v246
	v_exp_f32_e32 v247, v247
	v_add_f32_e32 v156, v156, v246
	v_add_f32_e32 v156, v156, v247
	v_cvt_pk_bf16_f32 v242, v246, v247
	v_exp_f32_e32 v248, v248
	v_exp_f32_e32 v249, v249
	v_add_f32_e32 v157, v157, v248
	v_add_f32_e32 v157, v157, v249
	v_cvt_pk_bf16_f32 v243, v248, v249
	v_exp_f32_e32 v250, v250
	v_exp_f32_e32 v251, v251
	v_add_f32_e32 v156, v156, v250
	v_add_f32_e32 v156, v156, v251
	v_cvt_pk_bf16_f32 v244, v250, v251
	v_exp_f32_e32 v252, v252
	v_exp_f32_e32 v253, v253
	v_add_f32_e32 v157, v157, v252
	v_add_f32_e32 v157, v157, v253
	v_cvt_pk_bf16_f32 v245, v252, v253
	v_exp_f32_e32 v180, v180
	v_exp_f32_e32 v181, v181
	v_add_f32_e32 v156, v156, v180
	v_add_f32_e32 v156, v156, v181
	v_cvt_pk_bf16_f32 v180, v180, v181
	v_exp_f32_e32 v182, v182
	v_exp_f32_e32 v183, v183
	v_add_f32_e32 v157, v157, v182
	v_add_f32_e32 v157, v157, v183
	v_cvt_pk_bf16_f32 v181, v182, v183
	v_exp_f32_e32 v184, v184
	v_exp_f32_e32 v185, v185
	v_add_f32_e32 v156, v156, v184
	v_add_f32_e32 v156, v156, v185
	v_cvt_pk_bf16_f32 v182, v184, v185
	v_exp_f32_e32 v186, v186
	v_exp_f32_e32 v187, v187
	v_add_f32_e32 v157, v157, v186
	v_add_f32_e32 v157, v157, v187
	v_cvt_pk_bf16_f32 v183, v186, v187
	v_exp_f32_e32 v188, v188
	v_exp_f32_e32 v189, v189
	v_add_f32_e32 v156, v156, v188
	v_add_f32_e32 v156, v156, v189
	v_cvt_pk_bf16_f32 v184, v188, v189
	v_exp_f32_e32 v190, v190
	v_exp_f32_e32 v191, v191
	v_add_f32_e32 v157, v157, v190
	v_add_f32_e32 v157, v157, v191
	v_cvt_pk_bf16_f32 v185, v190, v191
	v_exp_f32_e32 v192, v192
	v_exp_f32_e32 v193, v193
	v_add_f32_e32 v156, v156, v192
	v_add_f32_e32 v156, v156, v193
	v_cvt_pk_bf16_f32 v186, v192, v193
	v_exp_f32_e32 v194, v194
	v_exp_f32_e32 v195, v195
	v_add_f32_e32 v157, v157, v194
	v_add_f32_e32 v157, v157, v195
	v_cvt_pk_bf16_f32 v187, v194, v195
	v_add_f32_e32 v156, v156, v157
	v_add_f32_e32 v128, v128, v156
	s_waitcnt lgkmcnt(0)
	v_mfma_f32_32x32x16_bf16 v[18:33], v[238:241], v[196:199], v[18:33]
	v_mfma_f32_32x32x16_bf16 v[2:17], v[238:241], v[212:215], v[2:17]
	v_mfma_f32_32x32x16_bf16 v[18:33], v[242:245], v[200:203], v[18:33]
	v_mfma_f32_32x32x16_bf16 v[2:17], v[242:245], v[230:233], v[2:17]
	v_mfma_f32_32x32x16_bf16 v[18:33], v[180:183], v[204:207], v[18:33]
	v_mfma_f32_32x32x16_bf16 v[2:17], v[180:183], v[234:237], v[2:17]
	v_mfma_f32_32x32x16_bf16 v[18:33], v[184:187], v[208:211], v[18:33]
	v_mfma_f32_32x32x16_bf16 v[2:17], v[184:187], v[164:167], v[2:17]
	s_mov_b32 m0, s65
	v_mov_b32_e32 v122, v128
	s_mov_b64 s[38:39], 0
	s_branch .LBB0_936
.Lat_u2x_rare:
	s_nop 15
	v_max_f32_e32 v132, 0, v131
	v_exp_f32_e64 v133, -v132
	v_add_f32_e32 v130, v130, v132
	s_nop 0
	s_and_saveexec_b64 s[54:55], s[38:39]
	ds_write_b32 v147, v133
	s_or_b64 exec, exec, s[54:55]
	v_mul_f32_e32 v128, v128, v133
	v_sub_f32_e32 v104, v104, v132
	v_sub_f32_e32 v105, v105, v132
	v_sub_f32_e32 v106, v106, v132
	v_sub_f32_e32 v107, v107, v132
	v_sub_f32_e32 v108, v108, v132
	v_sub_f32_e32 v109, v109, v132
	v_sub_f32_e32 v110, v110, v132
	v_sub_f32_e32 v111, v111, v132
	v_sub_f32_e32 v112, v112, v132
	v_sub_f32_e32 v113, v113, v132
	v_sub_f32_e32 v114, v114, v132
	v_sub_f32_e32 v115, v115, v132
	v_sub_f32_e32 v116, v116, v132
	v_sub_f32_e32 v117, v117, v132
	v_sub_f32_e32 v118, v118, v132
	v_sub_f32_e32 v119, v119, v132
	v_sub_f32_e32 v238, v238, v132
	v_sub_f32_e32 v239, v239, v132
	v_sub_f32_e32 v240, v240, v132
	v_sub_f32_e32 v241, v241, v132
	v_sub_f32_e32 v242, v242, v132
	v_sub_f32_e32 v243, v243, v132
	v_sub_f32_e32 v244, v244, v132
	v_sub_f32_e32 v245, v245, v132
	v_sub_f32_e32 v246, v246, v132
	v_sub_f32_e32 v247, v247, v132
	v_sub_f32_e32 v248, v248, v132
	v_sub_f32_e32 v249, v249, v132
	v_sub_f32_e32 v250, v250, v132
	v_sub_f32_e32 v251, v251, v132
	v_sub_f32_e32 v252, v252, v132
	v_sub_f32_e32 v253, v253, v132
	v_sub_f32_e32 v180, v180, v132
	v_sub_f32_e32 v181, v181, v132
	v_sub_f32_e32 v182, v182, v132
	v_sub_f32_e32 v183, v183, v132
	v_sub_f32_e32 v184, v184, v132
	v_sub_f32_e32 v185, v185, v132
	v_sub_f32_e32 v186, v186, v132
	v_sub_f32_e32 v187, v187, v132
	v_sub_f32_e32 v188, v188, v132
	v_sub_f32_e32 v189, v189, v132
	v_sub_f32_e32 v190, v190, v132
	v_sub_f32_e32 v191, v191, v132
	v_sub_f32_e32 v192, v192, v132
	v_sub_f32_e32 v193, v193, v132
	v_sub_f32_e32 v194, v194, v132
	v_sub_f32_e32 v195, v195, v132
	s_waitcnt lgkmcnt(0)
	v_add_u32_e32 v133, s57, v129
	ds_read_b128 v[90:93], v133
	ds_read_b128 v[94:97], v133 offset:32
	ds_read_b128 v[98:101], v133 offset:64
	ds_read_b128 v[176:179], v133 offset:96
	s_waitcnt lgkmcnt(0)
	v_mul_f32_e32 v18, v18, v90
	v_mul_f32_e32 v2, v2, v90
	v_mul_f32_e32 v19, v19, v91
	v_mul_f32_e32 v3, v3, v91
	v_mul_f32_e32 v20, v20, v92
	v_mul_f32_e32 v4, v4, v92
	v_mul_f32_e32 v21, v21, v93
	v_mul_f32_e32 v5, v5, v93
	v_mul_f32_e32 v22, v22, v94
	v_mul_f32_e32 v6, v6, v94
	v_mul_f32_e32 v23, v23, v95
	v_mul_f32_e32 v7, v7, v95
	v_mul_f32_e32 v24, v24, v96
	v_mul_f32_e32 v8, v8, v96
	v_mul_f32_e32 v25, v25, v97
	v_mul_f32_e32 v9, v9, v97
	v_mul_f32_e32 v26, v26, v98
	v_mul_f32_e32 v10, v10, v98
	v_mul_f32_e32 v27, v27, v99
	v_mul_f32_e32 v11, v11, v99
	v_mul_f32_e32 v28, v28, v100
	v_mul_f32_e32 v12, v12, v100
	v_mul_f32_e32 v29, v29, v101
	v_mul_f32_e32 v13, v13, v101
	v_mul_f32_e32 v30, v30, v176
	v_mul_f32_e32 v14, v14, v176
	v_mul_f32_e32 v31, v31, v177
	v_mul_f32_e32 v15, v15, v177
	v_mul_f32_e32 v32, v32, v178
	v_mul_f32_e32 v16, v16, v178
	v_mul_f32_e32 v33, v33, v179
	v_mul_f32_e32 v17, v17, v179
	s_branch .Lat_u2x_back
.Lat_u2y_rare:
	s_nop 15
	v_max_f32_e32 v132, 0, v131
	v_exp_f32_e64 v133, -v132
	v_add_f32_e32 v130, v130, v132
	s_nop 0
	s_and_saveexec_b64 s[54:55], s[38:39]
	ds_write_b32 v147, v133
	s_or_b64 exec, exec, s[54:55]
	v_mul_f32_e32 v128, v128, v133
	v_sub_f32_e32 v104, v104, v132
	v_sub_f32_e32 v105, v105, v132
	v_sub_f32_e32 v106, v106, v132
	v_sub_f32_e32 v107, v107, v132
	v_sub_f32_e32 v108, v108, v132
	v_sub_f32_e32 v109, v109, v132
	v_sub_f32_e32 v110, v110, v132
	v_sub_f32_e32 v111, v111, v132
	v_sub_f32_e32 v112, v112, v132
	v_sub_f32_e32 v113, v113, v132
	v_sub_f32_e32 v114, v114, v132
	v_sub_f32_e32 v115, v115, v132
	v_sub_f32_e32 v116, v116, v132
	v_sub_f32_e32 v117, v117, v132
	v_sub_f32_e32 v118, v118, v132
	v_sub_f32_e32 v119, v119, v132
	v_sub_f32_e32 v50, v50, v132
	v_sub_f32_e32 v51, v51, v132
	v_sub_f32_e32 v52, v52, v132
	v_sub_f32_e32 v53, v53, v132
	v_sub_f32_e32 v54, v54, v132
	v_sub_f32_e32 v55, v55, v132
	v_sub_f32_e32 v56, v56, v132
	v_sub_f32_e32 v57, v57, v132
	v_sub_f32_e32 v58, v58, v132
	v_sub_f32_e32 v59, v59, v132
	v_sub_f32_e32 v60, v60, v132
	v_sub_f32_e32 v61, v61, v132
	v_sub_f32_e32 v62, v62, v132
	v_sub_f32_e32 v63, v63, v132
	v_sub_f32_e32 v64, v64, v132
	v_sub_f32_e32 v65, v65, v132
	v_sub_f32_e32 v34, v34, v132
	v_sub_f32_e32 v35, v35, v132
	v_sub_f32_e32 v36, v36, v132
	v_sub_f32_e32 v37, v37, v132
	v_sub_f32_e32 v38, v38, v132
	v_sub_f32_e32 v39, v39, v132
	v_sub_f32_e32 v40, v40, v132
	v_sub_f32_e32 v41, v41, v132
	v_sub_f32_e32 v42, v42, v132
	v_sub_f32_e32 v43, v43, v132
	v_sub_f32_e32 v44, v44, v132
	v_sub_f32_e32 v45, v45, v132
	v_sub_f32_e32 v46, v46, v132
	v_sub_f32_e32 v47, v47, v132
	v_sub_f32_e32 v48, v48, v132
	v_sub_f32_e32 v49, v49, v132
	s_waitcnt lgkmcnt(0)
	v_add_u32_e32 v133, s57, v129
	ds_read_b128 v[90:93], v133
	ds_read_b128 v[94:97], v133 offset:32
	ds_read_b128 v[98:101], v133 offset:64
	ds_read_b128 v[176:179], v133 offset:96
	s_waitcnt lgkmcnt(0)
	v_mul_f32_e32 v18, v18, v90
	v_mul_f32_e32 v2, v2, v90
	v_mul_f32_e32 v19, v19, v91
	v_mul_f32_e32 v3, v3, v91
	v_mul_f32_e32 v20, v20, v92
	v_mul_f32_e32 v4, v4, v92
	v_mul_f32_e32 v21, v21, v93
	v_mul_f32_e32 v5, v5, v93
	v_mul_f32_e32 v22, v22, v94
	v_mul_f32_e32 v6, v6, v94
	v_mul_f32_e32 v23, v23, v95
	v_mul_f32_e32 v7, v7, v95
	v_mul_f32_e32 v24, v24, v96
	v_mul_f32_e32 v8, v8, v96
	v_mul_f32_e32 v25, v25, v97
	v_mul_f32_e32 v9, v9, v97
	v_mul_f32_e32 v26, v26, v98
	v_mul_f32_e32 v10, v10, v98
	v_mul_f32_e32 v27, v27, v99
	v_mul_f32_e32 v11, v11, v99
	v_mul_f32_e32 v28, v28, v100
	v_mul_f32_e32 v12, v12, v100
	v_mul_f32_e32 v29, v29, v101
	v_mul_f32_e32 v13, v13, v101
	v_mul_f32_e32 v30, v30, v176
	v_mul_f32_e32 v14, v14, v176
	v_mul_f32_e32 v31, v31, v177
	v_mul_f32_e32 v15, v15, v177
	v_mul_f32_e32 v32, v32, v178
	v_mul_f32_e32 v16, v16, v178
	v_mul_f32_e32 v33, v33, v179
	v_mul_f32_e32 v17, v17, v179
	s_branch .Lat_u2y_back

; __device__ __forceinline__ unsigned xb_ld(unsigned* p)              { return __hip_atomic_load(p, __ATOMIC_RELAXED, __HIP_MEMORY_SCOPE_AGENT); }
; __device__ __forceinline__ unsigned xb_add(unsigned* p, unsigned v) { return __hip_atomic_fetch_add(p, v, __ATOMIC_RELAXED, __HIP_MEMORY_SCOPE_AGENT); }
; #define XB_SPIN(cond, bar) do { unsigned _sp = 0; while (cond) { __builtin_amdgcn_s_sleep(1); \
;     if ((++_sp & 255u) == 0u) { if (xb_ld(&(bar)[XB_TMO])) break; if (_sp > XB_SPIN_CAP) { atomicAdd(&(bar)[XB_TMO], 1u); break; } } } } while (0)
; __device__ __forceinline__ void xcd_local_barrier(const XcdBarrier& b, unsigned nloc) {
;     asm volatile("s_waitcnt vmcnt(0)" ::: "memory");
;     __syncthreads();
;     if (threadIdx.x == 0) {
;         unsigned* bar = b.bar;
;         __builtin_amdgcn_s_waitcnt(0);
;         const unsigned old = xb_add(&bar[XB_LSUB(b.x)], 1u);
;         const unsigned gen = old / nloc;
;         if (old + 1u == (gen + 1u) * nloc) xb_add(&bar[XB_LGEN(b.x)], 1u);
;         else XB_SPIN(xb_ld(&bar[XB_LGEN(b.x)]) == gen, bar);
;         __builtin_amdgcn_fence(__ATOMIC_ACQUIRE, "agent");
;         asm volatile("s_waitcnt vmcnt(0)" ::: "memory");
;     }
;     __syncthreads();
; }
.LBB0_975:
	s_setprio 0
	v_readlane_b32 s0, v254, 60
	v_mov_b32 v0, s0
	ds_read_b32 v0, v0
	s_waitcnt lgkmcnt(0)
	s_nop 0
	v_readfirstlane_b32 s0, v0
	s_cmp_eq_u32 s0, 0
	s_cbranch_scc1 .LBB0_989
	s_waitcnt vmcnt(0)
	s_waitcnt vmcnt(0) lgkmcnt(0)
	s_barrier
	s_and_saveexec_b64 s[0:1], s[92:93]
	v_readlane_b32 s50, v255, 5
	v_readlane_b32 s51, v255, 6
	s_cbranch_execz .LBB0_995
	s_add_u32 s101, s101, 32
	v_readlane_b32 s4, v254, 6
	v_readlane_b32 s5, v254, 7
	s_mov_b32 s100, 0
	s_nop 3
	global_atomic_add v1, v218, s[4:5]
	buffer_inv sc1

; __device__ __forceinline__ unsigned xb_ld(unsigned* p)              { return __hip_atomic_load(p, __ATOMIC_RELAXED, __HIP_MEMORY_SCOPE_AGENT); }
; __device__ __forceinline__ unsigned xb_add(unsigned* p, unsigned v) { return __hip_atomic_fetch_add(p, v, __ATOMIC_RELAXED, __HIP_MEMORY_SCOPE_AGENT); }
; #define XB_SPIN(cond, bar) do { unsigned _sp = 0; while (cond) { __builtin_amdgcn_s_sleep(1); \
;     if ((++_sp & 255u) == 0u) { if (xb_ld(&(bar)[XB_TMO])) break; if (_sp > XB_SPIN_CAP) { atomicAdd(&(bar)[XB_TMO], 1u); break; } } } } while (0)
; __device__ __forceinline__ void xcd_local_barrier(const XcdBarrier& b, unsigned nloc) {
;     asm volatile("s_waitcnt vmcnt(0)" ::: "memory");
;     __syncthreads();
;     if (threadIdx.x == 0) {
;         unsigned* bar = b.bar;
;         __builtin_amdgcn_s_waitcnt(0);
;         const unsigned old = xb_add(&bar[XB_LSUB(b.x)], 1u);
;         const unsigned gen = old / nloc;
;         if (old + 1u == (gen + 1u) * nloc) xb_add(&bar[XB_LGEN(b.x)], 1u);
;         else XB_SPIN(xb_ld(&bar[XB_LGEN(b.x)]) == gen, bar);
;         __builtin_amdgcn_fence(__ATOMIC_ACQUIRE, "agent");
;         asm volatile("s_waitcnt vmcnt(0)" ::: "memory");
;     }
;     __syncthreads();
; }
.Llb_done_2:
	s_branch .LBB0_995
.LBB0_989:
	v_readlane_b32 s50, v255, 5
	v_readlane_b32 s51, v255, 6
	s_cbranch_execnz .LBB0_996
	s_branch .LBB0_1049
.LBB0_995:
	s_or_b64 exec, exec, s[0:1]
	s_barrier
	s_branch .LBB0_1049

; __device__ __forceinline__ unsigned xb_ld(unsigned* p)              { return __hip_atomic_load(p, __ATOMIC_RELAXED, __HIP_MEMORY_SCOPE_AGENT); }
; __device__ __forceinline__ unsigned xb_add(unsigned* p, unsigned v) { return __hip_atomic_fetch_add(p, v, __ATOMIC_RELAXED, __HIP_MEMORY_SCOPE_AGENT); }
; #define XB_SPIN(cond, bar) do { unsigned _sp = 0; while (cond) { __builtin_amdgcn_s_sleep(1); \
;     if ((++_sp & 255u) == 0u) { if (xb_ld(&(bar)[XB_TMO])) break; if (_sp > XB_SPIN_CAP) { atomicAdd(&(bar)[XB_TMO], 1u); break; } } } } while (0)
; __device__ __forceinline__ void xcd_local_barrier(const XcdBarrier& b, unsigned nloc) {
;     asm volatile("s_waitcnt vmcnt(0)" ::: "memory");
;     __syncthreads();
;     if (threadIdx.x == 0) {
;         unsigned* bar = b.bar;
;         __builtin_amdgcn_s_waitcnt(0);
;         const unsigned old = xb_add(&bar[XB_LSUB(b.x)], 1u);
;         const unsigned gen = old / nloc;
;         if (old + 1u == (gen + 1u) * nloc) xb_add(&bar[XB_LGEN(b.x)], 1u);
;         else XB_SPIN(xb_ld(&bar[XB_LGEN(b.x)]) == gen, bar);
;         __builtin_amdgcn_fence(__ATOMIC_ACQUIRE, "agent");
;         asm volatile("s_waitcnt vmcnt(0)" ::: "memory");
;     }
;     __syncthreads();
; }
.LBB0_1367:
	v_readlane_b32 s0, v254, 60
	v_mov_b32 v0, s0
	ds_read_b32 v0, v0
	s_waitcnt lgkmcnt(0)
	s_nop 0
	v_readfirstlane_b32 s0, v0
	s_cmp_eq_u32 s0, 0
	s_cbranch_scc1 .LBB0_1381
	s_waitcnt vmcnt(0)
	s_waitcnt lgkmcnt(0)
	s_barrier
	s_and_saveexec_b64 s[0:1], s[92:93]
	v_readlane_b32 s58, v255, 17
	v_readlane_b32 s6, v255, 7
	v_readlane_b32 s52, v255, 9
	v_readlane_b32 s54, v255, 11
	v_readlane_b32 s56, v255, 13
	v_readlane_b32 s59, v255, 18
	v_readlane_b32 s7, v255, 8
	v_readlane_b32 s53, v255, 10
	v_readlane_b32 s55, v255, 12
	v_readlane_b32 s57, v255, 14
	s_cbranch_execz .LBB0_1387
	s_add_u32 s101, s101, 32
	v_readlane_b32 s4, v254, 6
	v_readlane_b32 s5, v254, 7
	s_mov_b32 s100, 0
	s_nop 3
	global_atomic_add v1, v218, s[4:5]
	buffer_inv sc1

; __device__ __forceinline__ unsigned xb_ld(unsigned* p)              { return __hip_atomic_load(p, __ATOMIC_RELAXED, __HIP_MEMORY_SCOPE_AGENT); }
; __device__ __forceinline__ unsigned xb_add(unsigned* p, unsigned v) { return __hip_atomic_fetch_add(p, v, __ATOMIC_RELAXED, __HIP_MEMORY_SCOPE_AGENT); }
; #define XB_SPIN(cond, bar) do { unsigned _sp = 0; while (cond) { __builtin_amdgcn_s_sleep(1); \
;     if ((++_sp & 255u) == 0u) { if (xb_ld(&(bar)[XB_TMO])) break; if (_sp > XB_SPIN_CAP) { atomicAdd(&(bar)[XB_TMO], 1u); break; } } } } while (0)
; __device__ __forceinline__ void xcd_local_barrier(const XcdBarrier& b, unsigned nloc) {
;     asm volatile("s_waitcnt vmcnt(0)" ::: "memory");
;     __syncthreads();
;     if (threadIdx.x == 0) {
;         unsigned* bar = b.bar;
;         __builtin_amdgcn_s_waitcnt(0);
;         const unsigned old = xb_add(&bar[XB_LSUB(b.x)], 1u);
;         const unsigned gen = old / nloc;
;         if (old + 1u == (gen + 1u) * nloc) xb_add(&bar[XB_LGEN(b.x)], 1u);
;         else XB_SPIN(xb_ld(&bar[XB_LGEN(b.x)]) == gen, bar);
;         __builtin_amdgcn_fence(__ATOMIC_ACQUIRE, "agent");
;         asm volatile("s_waitcnt vmcnt(0)" ::: "memory");
;     }
;     __syncthreads();
; }
.Llb_done_3:
	s_branch .LBB0_1387
.LBB0_1381:
	v_readlane_b32 s58, v255, 17
	v_readlane_b32 s6, v255, 7
	v_readlane_b32 s52, v255, 9
	v_readlane_b32 s54, v255, 11
	v_readlane_b32 s56, v255, 13
	v_readlane_b32 s59, v255, 18
	v_readlane_b32 s7, v255, 8
	v_readlane_b32 s53, v255, 10
	v_readlane_b32 s55, v255, 12
	v_readlane_b32 s57, v255, 14
	s_cbranch_execnz .LBB0_1388
	s_branch .LBB0_1441
.LBB0_1387:
	s_or_b64 exec, exec, s[0:1]
	s_barrier
	s_branch .LBB0_1441

; __device__ __forceinline__ unsigned xb_ld(unsigned* p)              { return __hip_atomic_load(p, __ATOMIC_RELAXED, __HIP_MEMORY_SCOPE_AGENT); }
; __device__ __forceinline__ unsigned xb_add(unsigned* p, unsigned v) { return __hip_atomic_fetch_add(p, v, __ATOMIC_RELAXED, __HIP_MEMORY_SCOPE_AGENT); }
; #define XB_SPIN(cond, bar) do { unsigned _sp = 0; while (cond) { __builtin_amdgcn_s_sleep(1); \
;     if ((++_sp & 255u) == 0u) { if (xb_ld(&(bar)[XB_TMO])) break; if (_sp > XB_SPIN_CAP) { atomicAdd(&(bar)[XB_TMO], 1u); break; } } } } while (0)
; __device__ __forceinline__ void xcd_local_barrier(const XcdBarrier& b, unsigned nloc) {
;     asm volatile("s_waitcnt vmcnt(0)" ::: "memory");
;     __syncthreads();
;     if (threadIdx.x == 0) {
;         unsigned* bar = b.bar;
;         __builtin_amdgcn_s_waitcnt(0);
;         const unsigned old = xb_add(&bar[XB_LSUB(b.x)], 1u);
;         const unsigned gen = old / nloc;
;         if (old + 1u == (gen + 1u) * nloc) xb_add(&bar[XB_LGEN(b.x)], 1u);
;         else XB_SPIN(xb_ld(&bar[XB_LGEN(b.x)]) == gen, bar);
;         __builtin_amdgcn_fence(__ATOMIC_ACQUIRE, "agent");
;         asm volatile("s_waitcnt vmcnt(0)" ::: "memory");
;     }
;     __syncthreads();
; }
.LBB0_1467:
	v_readlane_b32 s0, v254, 60
	v_mov_b32 v0, s0
	ds_read_b32 v0, v0
	s_waitcnt lgkmcnt(0)
	s_nop 0
	v_readfirstlane_b32 s0, v0
	s_cmp_eq_u32 s0, 0
	s_cbranch_scc1 .LBB0_1481
	s_waitcnt vmcnt(0)
	s_waitcnt vmcnt(0) lgkmcnt(0)
	s_barrier
	s_and_saveexec_b64 s[0:1], s[92:93]
	s_cbranch_execz .LBB0_1487
	s_add_u32 s101, s101, 32
	v_readlane_b32 s4, v254, 6
	v_readlane_b32 s5, v254, 7
	s_mov_b32 s100, 0
	s_nop 3
	global_atomic_add v1, v218, s[4:5]
	buffer_inv sc1

; __device__ __forceinline__ unsigned xb_ld(unsigned* p)              { return __hip_atomic_load(p, __ATOMIC_RELAXED, __HIP_MEMORY_SCOPE_AGENT); }
; __device__ __forceinline__ unsigned xb_add(unsigned* p, unsigned v) { return __hip_atomic_fetch_add(p, v, __ATOMIC_RELAXED, __HIP_MEMORY_SCOPE_AGENT); }
; #define XB_SPIN(cond, bar) do { unsigned _sp = 0; while (cond) { __builtin_amdgcn_s_sleep(1); \
;     if ((++_sp & 255u) == 0u) { if (xb_ld(&(bar)[XB_TMO])) break; if (_sp > XB_SPIN_CAP) { atomicAdd(&(bar)[XB_TMO], 1u); break; } } } } while (0)
; __device__ __forceinline__ void xcd_local_barrier(const XcdBarrier& b, unsigned nloc) {
;     asm volatile("s_waitcnt vmcnt(0)" ::: "memory");
;     __syncthreads();
;     if (threadIdx.x == 0) {
;         unsigned* bar = b.bar;
;         __builtin_amdgcn_s_waitcnt(0);
;         const unsigned old = xb_add(&bar[XB_LSUB(b.x)], 1u);
;         const unsigned gen = old / nloc;
;         if (old + 1u == (gen + 1u) * nloc) xb_add(&bar[XB_LGEN(b.x)], 1u);
;         else XB_SPIN(xb_ld(&bar[XB_LGEN(b.x)]) == gen, bar);
;         __builtin_amdgcn_fence(__ATOMIC_ACQUIRE, "agent");
;         asm volatile("s_waitcnt vmcnt(0)" ::: "memory");
;     }
;     __syncthreads();
; }
.Llb_done_4:
	s_branch .LBB0_1487
.LBB0_1481:
	v_readlane_b32 s44, v255, 9
	v_readlane_b32 s46, v255, 11
	v_readlane_b32 s52, v255, 13
	v_readlane_b32 s45, v255, 10
	v_readlane_b32 s47, v255, 12
	v_readlane_b32 s53, v255, 14
	s_cbranch_execnz .LBB0_1488
	s_branch .LBB0_1541
.LBB0_1487:
	s_or_b64 exec, exec, s[0:1]
	v_readlane_b32 s44, v255, 9
	v_readlane_b32 s46, v255, 11
	v_readlane_b32 s52, v255, 13
	v_readlane_b32 s45, v255, 10
	v_readlane_b32 s47, v255, 12
	v_readlane_b32 s53, v255, 14
	s_barrier
	s_branch .LBB0_1541

; __device__ __forceinline__ unsigned xb_ld(unsigned* p)              { return __hip_atomic_load(p, __ATOMIC_RELAXED, __HIP_MEMORY_SCOPE_AGENT); }
; __device__ __forceinline__ unsigned xb_add(unsigned* p, unsigned v) { return __hip_atomic_fetch_add(p, v, __ATOMIC_RELAXED, __HIP_MEMORY_SCOPE_AGENT); }
; #define XB_SPIN(cond, bar) do { unsigned _sp = 0; while (cond) { __builtin_amdgcn_s_sleep(1); \
;     if ((++_sp & 255u) == 0u) { if (xb_ld(&(bar)[XB_TMO])) break; if (_sp > XB_SPIN_CAP) { atomicAdd(&(bar)[XB_TMO], 1u); break; } } } } while (0)
; #define GRID_BAR() xcd_barrier(bar)
; #define SEAM_LOCAL() do { if (__builtin_amdgcn_readfirstlane((int)lds_word((unsigned)(__UINTPTR_TYPE__)lds + MISC_OFF + 68))) xcd_local_barrier(bar, 32u); else xcd_barrier(bar); } while (0)
; __device__ __forceinline__ void xcd_local_barrier(const XcdBarrier& b, unsigned nloc) {
;     asm volatile("s_waitcnt vmcnt(0)" ::: "memory");
;     __syncthreads();
;     if (threadIdx.x == 0) {
;         unsigned* bar = b.bar;
;         __builtin_amdgcn_s_waitcnt(0);
;         const unsigned old = xb_add(&bar[XB_LSUB(b.x)], 1u);
;         const unsigned gen = old / nloc;
;         if (old + 1u == (gen + 1u) * nloc) xb_add(&bar[XB_LGEN(b.x)], 1u);
;         else XB_SPIN(xb_ld(&bar[XB_LGEN(b.x)]) == gen, bar);
;         __builtin_amdgcn_fence(__ATOMIC_ACQUIRE, "agent");
;         asm volatile("s_waitcnt vmcnt(0)" ::: "memory");
;     }
;     __syncthreads();
; }
; __global__ void __launch_bounds__(512, 2) trunk_fwd(Args args) {
;     ...
;         if (L + 1 < DEPTH) SEAM_LOCAL(); else GRID_BAR();
.LBB0_1587:
	v_readlane_b32 s0, v255, 19
	v_readlane_b32 s1, v255, 20
	v_readlane_b32 s78, v255, 7
	v_readlane_b32 s6, v255, 9
	v_cndmask_b32_e64 v0, 0, 1, s[0:1]
	v_readlane_b32 s52, v255, 11
	v_readlane_b32 s54, v255, 13
	v_cmp_ne_u32_e64 s[44:45], 1, v0
	s_andn2_b64 vcc, exec, s[0:1]
	s_mov_b64 s[0:1], -1
	v_readlane_b32 s79, v255, 8
	v_readlane_b32 s7, v255, 10
	v_readlane_b32 s53, v255, 12
	v_readlane_b32 s55, v255, 14
	s_cbranch_vccnz .LBB0_1663
	v_readlane_b32 s0, v254, 60
	v_mov_b32 v0, s0
	ds_read_b32 v0, v0
	s_waitcnt lgkmcnt(0)
	s_nop 0
	v_readfirstlane_b32 s0, v0
	s_cmp_eq_u32 s0, 0
	s_cbranch_scc1 .LBB0_1602
	s_waitcnt vmcnt(0)
	s_waitcnt vmcnt(0) lgkmcnt(0)
	s_barrier
	s_and_saveexec_b64 s[0:1], s[92:93]
	s_cbranch_execz .LBB0_1608
	s_add_u32 s101, s101, 32
	v_readlane_b32 s4, v254, 6
	v_readlane_b32 s5, v254, 7
	s_mov_b32 s100, 0
	s_nop 3
	global_atomic_add v1, v218, s[4:5]
	buffer_inv sc1

; __device__ __forceinline__ unsigned xb_ld(unsigned* p)              { return __hip_atomic_load(p, __ATOMIC_RELAXED, __HIP_MEMORY_SCOPE_AGENT); }
; __device__ __forceinline__ unsigned xb_add(unsigned* p, unsigned v) { return __hip_atomic_fetch_add(p, v, __ATOMIC_RELAXED, __HIP_MEMORY_SCOPE_AGENT); }
; #define XB_SPIN(cond, bar) do { unsigned _sp = 0; while (cond) { __builtin_amdgcn_s_sleep(1); \
;     if ((++_sp & 255u) == 0u) { if (xb_ld(&(bar)[XB_TMO])) break; if (_sp > XB_SPIN_CAP) { atomicAdd(&(bar)[XB_TMO], 1u); break; } } } } while (0)
; __device__ __forceinline__ void xcd_local_barrier(const XcdBarrier& b, unsigned nloc) {
;     asm volatile("s_waitcnt vmcnt(0)" ::: "memory");
;     __syncthreads();
;     if (threadIdx.x == 0) {
;         unsigned* bar = b.bar;
;         __builtin_amdgcn_s_waitcnt(0);
;         const unsigned old = xb_add(&bar[XB_LSUB(b.x)], 1u);
;         const unsigned gen = old / nloc;
;         if (old + 1u == (gen + 1u) * nloc) xb_add(&bar[XB_LGEN(b.x)], 1u);
;         else XB_SPIN(xb_ld(&bar[XB_LGEN(b.x)]) == gen, bar);
;         __builtin_amdgcn_fence(__ATOMIC_ACQUIRE, "agent");
;         asm volatile("s_waitcnt vmcnt(0)" ::: "memory");
;     }
;     __syncthreads();
; }
.Llb_done_5:
	s_branch .LBB0_1608
.LBB0_1602:
	s_cbranch_execnz .LBB0_1609
	s_branch .LBB0_1662
.LBB0_1608:
	s_or_b64 exec, exec, s[0:1]
	s_barrier
	s_branch .LBB0_1662

; __global__ void __launch_bounds__(512, 2) trunk_fwd(Args args) {
	.amdhsa_kernel _Z9trunk_fwd4Args
		.amdhsa_group_segment_fixed_size 0
		.amdhsa_private_segment_fixed_size 0
		.amdhsa_kernarg_size 456
		.amdhsa_user_sgpr_count 2
		.amdhsa_user_sgpr_dispatch_ptr 0
		.amdhsa_user_sgpr_queue_ptr 0
		.amdhsa_user_sgpr_kernarg_segment_ptr 1
		.amdhsa_user_sgpr_dispatch_id 0
		.amdhsa_user_sgpr_kernarg_preload_length 0
		.amdhsa_user_sgpr_kernarg_preload_offset 0
		.amdhsa_user_sgpr_private_segment_size 0
		.amdhsa_uses_dynamic_stack 0
		.amdhsa_enable_private_segment 0
		.amdhsa_system_sgpr_workgroup_id_x 1
		.amdhsa_system_sgpr_workgroup_id_y 0
		.amdhsa_system_sgpr_workgroup_id_z 0
		.amdhsa_system_sgpr_workgroup_info 0
		.amdhsa_system_vgpr_workitem_id 2
		.amdhsa_next_free_vgpr 256
		.amdhsa_next_free_sgpr 102
		.amdhsa_accum_offset 256
		.amdhsa_reserve_vcc 1
		.amdhsa_float_round_mode_32 0
		.amdhsa_float_round_mode_16_64 0
		.amdhsa_float_denorm_mode_32 3
		.amdhsa_float_denorm_mode_16_64 3
		.amdhsa_dx10_clamp 1
		.amdhsa_ieee_mode 1
		.amdhsa_fp16_overflow 0
		.amdhsa_tg_split 0
		.amdhsa_exception_fp_ieee_invalid_op 0
		.amdhsa_exception_fp_denorm_src 0
		.amdhsa_exception_fp_ieee_div_zero 0
		.amdhsa_exception_fp_ieee_overflow 0
		.amdhsa_exception_fp_ieee_underflow 0
		.amdhsa_exception_fp_ieee_inexact 0
		.amdhsa_exception_int_div_zero 0
	.end_amdhsa_kernel

; __global__ void __launch_bounds__(512, 2) trunk_fwd(Args args) {
amdhsa.kernels:
  - .agpr_count:     0
    .args:
      - .offset:         0
        .size:           200
        .value_kind:     by_value
      - .offset:         200
        .size:           4
        .value_kind:     hidden_block_count_x
      - .offset:         204
        .size:           4
        .value_kind:     hidden_block_count_y
      - .offset:         208
        .size:           4
        .value_kind:     hidden_block_count_z
      - .offset:         212
        .size:           2
        .value_kind:     hidden_group_size_x
      - .offset:         214
        .size:           2
        .value_kind:     hidden_group_size_y
      - .offset:         216
        .size:           2
        .value_kind:     hidden_group_size_z
      - .offset:         218
        .size:           2
        .value_kind:     hidden_remainder_x
      - .offset:         220
        .size:           2
        .value_kind:     hidden_remainder_y
      - .offset:         222
        .size:           2
        .value_kind:     hidden_remainder_z
      - .offset:         240
        .size:           8
        .value_kind:     hidden_global_offset_x
      - .offset:         248
        .size:           8
        .value_kind:     hidden_global_offset_y
      - .offset:         256
        .size:           8
        .value_kind:     hidden_global_offset_z
      - .offset:         264
        .size:           2
        .value_kind:     hidden_grid_dims
      - .offset:         288
        .size:           8
        .value_kind:     hidden_multigrid_sync_arg
      - .offset:         320
        .size:           4
        .value_kind:     hidden_dynamic_lds_size
    .group_segment_fixed_size: 0
    .kernarg_segment_align: 8
    .kernarg_segment_size: 456
    .language:       OpenCL C
    .language_version:
      - 2
      - 0
    .max_flat_workgroup_size: 512
    .name:           _Z9trunk_fwd4Args
    .private_segment_fixed_size: 0
    .sgpr_count:     108
    .sgpr_spill_count: 106
    .symbol:         _Z9trunk_fwd4Args.kd
    .uniform_work_group_size: 1
    .uses_dynamic_stack: false
    .vgpr_count:     256
    .vgpr_spill_count: 0
    .wavefront_size: 64
